# stack4 + attention: Q fragments kept in the 16 VGPRs the pass-1 epilogue leaves free instead of re-read from LDS each KV step; steady-loop LDS waits re-derived per consumer; step barrier leaves the ne
# baseline (speedup 1.0000x reference)
.LBB0_313:
	v_mov_b32_e32 v0, v223
	s_or_b32 s88, s0, s67
	s_lshl_b64 s[0:1], s[88:89], 1
	v_lshlrev_b32_e32 v2, 9, v0
	v_ashrrev_i32_e32 v0, 2, v0
	s_add_u32 s0, s77, s0
	v_and_b32_e32 v2, 0x3e00, v2
	v_and_b32_e32 v0, -8, v0
	s_addc_u32 s1, s78, s1
	v_add_u32_e32 v0, v2, v0
	v_lshl_add_u64 v[14:15], v[0:1], 1, s[0:1]
	global_load_dwordx4 v[130:133], v[14:15], off
	global_load_dwordx4 v[134:137], v[14:15], off offset:32
	global_load_dwordx4 v[138:141], v[14:15], off offset:64
	global_load_dwordx4 v[142:145], v[14:15], off offset:96
	v_add_u32_e32 v213, s74, v235
	s_mov_b64 s[0:1], -1
	s_and_b64 vcc, exec, s[48:49]
	s_waitcnt vmcnt(3)
	s_waitcnt vmcnt(2)
	s_waitcnt vmcnt(1)
	s_waitcnt vmcnt(0)
	s_cbranch_vccz .LBB0_315
	s_waitcnt vmcnt(0) lgkmcnt(0)
	s_barrier
	s_mov_b64 s[0:1], 0

.LBB0_317:
	ds_read_b128 v[14:17], v233
	ds_read_b128 v[34:37], v233 offset:512
	s_cmp_lg_u32 0, -1
	s_cselect_b32 s0, 0, 0
	s_add_i32 s0, s0, s70
	s_waitcnt lgkmcnt(1)
	v_mfma_f32_32x32x16_bf16 v[18:33], v[14:17], v[130:133], 0
	s_add_i32 s1, s0, 0x6000
	s_mov_b32 s4, 0
	s_mov_b32 s5, s4
	s_mov_b32 s6, s4
	s_mov_b32 s7, s4
	s_mov_b32 s8, s4
	s_mov_b32 s9, s4
	s_waitcnt lgkmcnt(0)
	v_mfma_f32_32x32x16_bf16 v[34:49], v[34:37], v[130:133], 0
	ds_read_b128 v[10:13], v233 offset:2048
	ds_read_b128 v[14:17], v233 offset:2560
	s_mov_b32 s10, s4
	s_mov_b32 s11, s4
	s_mov_b32 s12, s4
	s_mov_b32 s13, s4
	s_mov_b32 s14, s4
	s_mov_b32 s15, s4
	s_waitcnt lgkmcnt(1)
	v_mfma_f32_32x32x16_bf16 v[18:33], v[10:13], v[134:137], v[18:33]
	s_mov_b32 s16, s4
	s_mov_b32 s17, s4
	s_mov_b32 s18, s4
	s_mov_b32 s19, s4
	v_mov_b32_e32 v214, 0
	s_waitcnt lgkmcnt(0)
	v_mfma_f32_32x32x16_bf16 v[34:49], v[14:17], v[134:137], v[34:49]
	ds_read_b128 v[6:9], v233 offset:4096
	ds_read_b128 v[10:13], v233 offset:4608
	s_waitcnt lgkmcnt(1)
	v_mfma_f32_32x32x16_bf16 v[18:33], v[6:9], v[138:141], v[18:33]
	ds_read_b128 v[6:9], v233 offset:6144
	ds_read_b128 v[54:57], v233 offset:6656
	s_waitcnt vmcnt(0) lgkmcnt(0)
	s_barrier
	s_mov_b32 s2, m0
	s_mov_b32 m0, s1
	s_nop 3
	global_load_lds_dwordx4 v210, s[46:47]
	s_mov_b32 m0, s2
	s_add_u32 s46, s46, 0x10000
	s_addc_u32 s47, s47, 0
	s_add_i32 s1, s0, 0xc000
	s_mov_b32 s2, m0
	s_mov_b32 m0, s1
	s_nop 3
	global_load_lds_dwordx4 v211, s[44:45]
	s_mov_b32 m0, s2
	s_waitcnt lgkmcnt(2)
	v_mfma_f32_32x32x16_bf16 v[34:49], v[10:13], v[138:141], v[34:49]
	s_add_i32 s0, s0, 0xe000
	s_mov_b32 s1, m0
	s_mov_b32 m0, s0
	s_nop 3
	global_load_lds_dwordx4 v212, s[44:45]
	s_mov_b32 m0, s1
	ds_read_b128 v[190:193], v233 offset:8192
	ds_read_b128 v[182:185], v233 offset:8704
	ds_read_b128 v[186:189], v233 offset:10240
	ds_read_b128 v[178:181], v233 offset:10752
	s_add_u32 s44, s44, 0x10000
	s_addc_u32 s45, s45, 0
	s_waitcnt lgkmcnt(5)
	v_mfma_f32_32x32x16_bf16 v[18:33], v[6:9], v[142:145], v[18:33]
	v_mov_b64_e32 v[2:3], s[4:5]
	v_mov_b64_e32 v[16:17], s[18:19]
	v_mov_b64_e32 v[4:5], s[6:7]
	v_mov_b64_e32 v[6:7], s[8:9]
	v_mov_b64_e32 v[8:9], s[10:11]
	v_mov_b64_e32 v[10:11], s[12:13]
	v_mov_b64_e32 v[12:13], s[14:15]
	s_waitcnt lgkmcnt(4)
	v_mfma_f32_32x32x16_bf16 v[34:49], v[54:57], v[142:145], v[34:49]
	s_nop 2
	v_max_f32_e32 v0, v19, v19
	v_max_f32_e32 v58, v18, v18
	v_max_f32_e32 v0, v58, v0
	v_mov_b64_e32 v[14:15], s[16:17]
	s_mov_b32 s6, -1
	s_mov_b32 s5, 0x8000
	s_movk_i32 s12, 0x4000
	s_nop 1
	v_max3_f32 v50, v20, v21, v35
	v_max3_f32 v0, v0, v34, v36
	v_max3_f32 v0, v0, v37, v22
	v_max3_f32 v50, v50, v24, v25
	v_max3_f32 v0, v0, v23, v38
	v_max3_f32 v50, v50, v40, v41
	v_max3_f32 v0, v0, v39, v26
	v_max3_f32 v50, v50, v28, v29
	v_max3_f32 v0, v0, v27, v42
	v_max3_f32 v50, v50, v44, v45
	v_max3_f32 v0, v0, v43, v30
	v_max3_f32 v50, v50, v32, v33
	v_max3_f32 v0, v0, v31, v46
	v_max3_f32 v50, v50, v48, v49
	v_max3_f32 v0, v0, v47, v50
	v_mov_b32_e32 v50, v0
	s_nop 1
	v_permlane32_swap_b32_e32 v0, v50
	v_max_f32_e32 v50, v50, v50
	v_max_f32_e32 v0, v0, v0
	v_max_f32_e32 v0, v0, v50
	v_sub_f32_e32 v18, v18, v0
	v_exp_f32_e32 v82, v18
	v_sub_f32_e32 v18, v34, v0
	v_exp_f32_e32 v66, v18
	v_sub_f32_e32 v18, v19, v0
	v_exp_f32_e32 v83, v18
	v_sub_f32_e32 v18, v35, v0
	v_exp_f32_e32 v67, v18
	v_sub_f32_e32 v18, v20, v0
	v_exp_f32_e32 v84, v18
	v_sub_f32_e32 v18, v36, v0
	v_exp_f32_e32 v68, v18
	v_sub_f32_e32 v18, v21, v0
	v_exp_f32_e32 v85, v18
	v_sub_f32_e32 v18, v37, v0
	v_exp_f32_e32 v69, v18
	v_sub_f32_e32 v18, v22, v0
	v_exp_f32_e32 v86, v18
	v_sub_f32_e32 v18, v38, v0
	v_exp_f32_e32 v70, v18
	v_sub_f32_e32 v18, v23, v0
	v_exp_f32_e32 v87, v18
	v_sub_f32_e32 v18, v39, v0
	v_exp_f32_e32 v71, v18
	v_sub_f32_e32 v18, v24, v0
	v_exp_f32_e32 v88, v18
	v_sub_f32_e32 v18, v40, v0
	v_exp_f32_e32 v72, v18
	v_sub_f32_e32 v18, v25, v0
	v_exp_f32_e32 v89, v18
	v_sub_f32_e32 v18, v41, v0
	v_exp_f32_e32 v73, v18
	v_sub_f32_e32 v18, v26, v0
	v_exp_f32_e32 v90, v18
	v_sub_f32_e32 v18, v42, v0
	v_exp_f32_e32 v74, v18
	v_sub_f32_e32 v18, v27, v0
	v_exp_f32_e32 v91, v18
	v_sub_f32_e32 v18, v43, v0
	v_exp_f32_e32 v75, v18
	v_sub_f32_e32 v18, v28, v0
	v_exp_f32_e32 v92, v18
	v_sub_f32_e32 v18, v44, v0
	v_exp_f32_e32 v76, v18
	v_sub_f32_e32 v18, v29, v0
	v_exp_f32_e32 v93, v18
	v_sub_f32_e32 v18, v45, v0
	v_exp_f32_e32 v77, v18
	v_sub_f32_e32 v18, v30, v0
	v_exp_f32_e32 v94, v18
	v_sub_f32_e32 v18, v46, v0
	v_exp_f32_e32 v78, v18
	v_sub_f32_e32 v18, v31, v0
	v_exp_f32_e32 v95, v18
	v_sub_f32_e32 v18, v47, v0
	v_exp_f32_e32 v79, v18
	v_sub_f32_e32 v18, v32, v0
	v_exp_f32_e32 v96, v18
	v_sub_f32_e32 v18, v48, v0
	v_exp_f32_e32 v80, v18
	v_sub_f32_e32 v18, v33, v0
	v_exp_f32_e32 v97, v18
	v_sub_f32_e32 v18, v49, v0
	v_exp_f32_e32 v81, v18
	v_mov_b64_e32 v[64:65], v[16:17]
	v_mov_b64_e32 v[48:49], v[16:17]
	v_mov_b64_e32 v[32:33], v[16:17]
	s_movk_i32 s15, 0x2000
	s_mov_b32 s8, 5
	s_mov_b32 s10, s79
	v_mov_b64_e32 v[62:63], v[14:15]
	v_mov_b64_e32 v[60:61], v[12:13]
	v_mov_b64_e32 v[58:59], v[10:11]
	v_mov_b64_e32 v[56:57], v[8:9]
	v_mov_b64_e32 v[54:55], v[6:7]
	v_mov_b64_e32 v[52:53], v[4:5]
	v_mov_b64_e32 v[50:51], v[2:3]
	v_mov_b64_e32 v[46:47], v[14:15]
	v_mov_b64_e32 v[44:45], v[12:13]
	v_mov_b64_e32 v[42:43], v[10:11]
	v_mov_b64_e32 v[40:41], v[8:9]
	v_mov_b64_e32 v[38:39], v[6:7]
	v_mov_b64_e32 v[36:37], v[4:5]
	v_mov_b64_e32 v[34:35], v[2:3]
	v_mov_b64_e32 v[30:31], v[14:15]
	v_mov_b64_e32 v[28:29], v[12:13]
	v_mov_b64_e32 v[26:27], v[10:11]
	v_mov_b64_e32 v[24:25], v[8:9]
	v_mov_b64_e32 v[22:23], v[6:7]
	v_mov_b64_e32 v[20:21], v[4:5]
	v_mov_b64_e32 v[18:19], v[2:3]
	s_movk_i32 s7, 0x4000
	s_waitcnt lgkmcnt(0)
.LBB0_318:
	v_add_u32_e32 v202, s4, v234
	v_add_u32_e32 v162, s15, v233
	ds_read_b64_tr_b16 v[200:201], v202 offset:33280
	ds_read_b128 v[204:207], v162 offset:4096
	ds_read_b64_tr_b16 v[198:199], v202 offset:32768
	s_waitcnt lgkmcnt(6)
	v_mfma_f32_32x32x16_bf16 v[114:129], v[190:193], v[130:133], 0
	v_add_f32_e32 v98, v82, v83
	v_add_f32_e32 v98, v84, v98
	v_add_f32_e32 v98, v85, v98
	v_add_f32_e32 v98, v86, v98
	v_add_f32_e32 v98, v87, v98
	v_cvt_pk_bf16_f32 v174, v82, v83
	v_cvt_pk_bf16_f32 v175, v84, v85
	ds_read_b64_tr_b16 v[190:191], v202 offset:36864
	ds_read_b64_tr_b16 v[192:193], v202 offset:37376
	ds_read_b128 v[236:239], v162 offset:4608
	v_add_f32_e32 v82, v88, v98
	s_waitcnt lgkmcnt(8)
	v_mfma_f32_32x32x16_bf16 v[98:113], v[182:185], v[130:133], 0
	v_add_f32_e32 v82, v89, v82
	v_add_f32_e32 v82, v90, v82
	v_add_f32_e32 v163, v91, v82
	v_cvt_pk_bf16_f32 v176, v86, v87
	v_cvt_pk_bf16_f32 v177, v88, v89
	ds_read_b64_tr_b16 v[84:85], v202 offset:34304
	ds_read_b128 v[182:185], v162 offset:6144
	ds_read_b64_tr_b16 v[82:83], v202 offset:33792
	s_waitcnt lgkmcnt(10)
	v_mfma_f32_32x32x16_bf16 v[114:129], v[186:189], v[134:137], v[114:129]
	v_add_f32_e32 v86, v92, v163
	v_add_f32_e32 v86, v93, v86
	v_add_f32_e32 v86, v94, v86
	v_add_f32_e32 v163, v95, v86
	v_cvt_pk_bf16_f32 v170, v90, v91
	v_cvt_pk_bf16_f32 v171, v92, v93
	ds_read_b64_tr_b16 v[86:87], v202 offset:37888
	ds_read_b64_tr_b16 v[88:89], v202 offset:38400
	ds_read_b128 v[186:189], v162 offset:6656
	s_waitcnt lgkmcnt(12)
	v_mfma_f32_32x32x16_bf16 v[98:113], v[178:181], v[134:137], v[98:113]
	v_add_f32_e32 v90, v96, v163
	v_add_f32_e32 v90, v97, v90
	v_add_f32_e32 v90, v66, v90
	v_add_f32_e32 v162, v67, v90
	v_cvt_pk_bf16_f32 v172, v94, v95
	v_cvt_pk_bf16_f32 v173, v96, v97
	ds_read_b64_tr_b16 v[92:93], v202 offset:35328
	ds_read_b64_tr_b16 v[90:91], v202 offset:34816
	s_waitcnt lgkmcnt(12)
	v_mfma_f32_32x32x16_bf16 v[114:129], v[204:207], v[138:141], v[114:129]
	v_add_f32_e32 v94, v68, v162
	v_add_f32_e32 v94, v69, v94
	v_add_f32_e32 v94, v70, v94
	v_add_f32_e32 v162, v71, v94
	v_cvt_pk_bf16_f32 v166, v66, v67
	v_cvt_pk_bf16_f32 v167, v68, v69
	ds_read_b64_tr_b16 v[94:95], v202 offset:38912
	ds_read_b64_tr_b16 v[96:97], v202 offset:39424
	s_waitcnt lgkmcnt(10)
	v_mfma_f32_32x32x16_bf16 v[98:113], v[236:239], v[138:141], v[98:113]
	v_add_f32_e32 v66, v72, v162
	v_add_f32_e32 v66, v73, v66
	v_add_f32_e32 v66, v74, v66
	v_add_f32_e32 v66, v75, v66
	v_cvt_pk_bf16_f32 v168, v70, v71
	v_cvt_pk_bf16_f32 v169, v72, v73
	ds_read_b64_tr_b16 v[70:71], v202 offset:35840
	ds_read_b64_tr_b16 v[72:73], v202 offset:36352
	s_waitcnt lgkmcnt(10)
	v_mfma_f32_32x32x16_bf16 v[114:129], v[182:185], v[142:145], v[114:129]
	v_add_f32_e32 v66, v76, v66
	v_add_f32_e32 v66, v77, v66
	v_add_f32_e32 v66, v78, v66
	v_add_f32_e32 v182, v79, v66
	v_cvt_pk_bf16_f32 v162, v74, v75
	v_cvt_pk_bf16_f32 v163, v76, v77
	ds_read_b64_tr_b16 v[66:67], v202 offset:39936
	ds_read_b64_tr_b16 v[68:69], v202 offset:40448
	s_waitcnt lgkmcnt(8)
	v_mfma_f32_32x32x16_bf16 v[98:113], v[186:189], v[142:145], v[98:113]
	v_add_f32_e32 v74, v80, v182
	v_add_f32_e32 v74, v81, v74
	v_add_f32_e32 v74, 0, v74
	v_cvt_pk_bf16_f32 v164, v78, v79
	v_cvt_pk_bf16_f32 v165, v80, v81
	s_nop 0
	v_add_f32_e32 v194, v214, v74
	v_max_f32_e32 v74, v115, v115
	v_max_f32_e32 v75, v114, v114
	v_max_f32_e32 v74, v75, v74
	s_nop 1
	v_max3_f32 v75, v116, v117, v99
	v_max3_f32 v74, v74, v98, v100
	v_max3_f32 v74, v74, v101, v118
	v_max3_f32 v75, v75, v120, v121
	v_max3_f32 v74, v74, v119, v102
	v_max3_f32 v75, v75, v104, v105
	v_max3_f32 v74, v74, v103, v122
	v_max3_f32 v75, v75, v124, v125
	v_max3_f32 v74, v74, v123, v106
	v_max3_f32 v75, v75, v108, v109
	v_max3_f32 v74, v74, v107, v126
	v_max3_f32 v75, v75, v128, v129
	v_max3_f32 v74, v74, v127, v110
	v_max3_f32 v75, v75, v112, v113
	v_max3_f32 v74, v74, v111, v75
	s_add_i32 s0, s15, 0xffffe000
	v_mov_b32_e32 v75, v74
	s_cmp_lg_u32 s15, 0
	s_nop 0
	v_permlane32_swap_b32_e32 v74, v75
	s_cselect_b32 s0, s0, 0x6000
	v_max_f32_e32 v75, v75, v75
	v_max_f32_e32 v74, v74, v74
	s_add_i32 s0, s0, s71
	s_mov_b32 s1, m0
	s_mov_b32 m0, s0
	s_nop 3
	global_load_lds_dwordx4 v210, s[46:47]
	s_mov_b32 m0, s1
	v_max_f32_e32 v74, v74, v75
	s_add_i32 s0, s5, s72
	s_mov_b32 s1, m0
	s_mov_b32 m0, s0
	s_nop 3
	global_load_lds_dwordx4 v211, s[44:45]
	s_mov_b32 m0, s1
	v_sub_f32_e32 v74, v74, v0
	s_addk_i32 s0, 0x2000
	s_mov_b32 s1, m0
	s_mov_b32 m0, s0
	s_nop 3
	global_load_lds_dwordx4 v212, s[44:45]
	s_mov_b32 m0, s1
	v_cmp_lt_f32_e32 vcc, s87, v74
	s_cmp_lg_u64 vcc, 0
	s_cselect_b64 s[0:1], -1, 0
	s_cbranch_vccnz .LBB0_326
.LBB0_319:
	v_mfma_f32_32x32x16_bf16 v[2:17], v[174:177], v[198:201], v[2:17]
	v_sub_f32_e32 v74, v114, v0
	v_exp_f32_e32 v114, v74
	v_sub_f32_e32 v74, v115, v0
	v_exp_f32_e32 v115, v74
	ds_read_b64_tr_b16 v[74:75], v202 offset:40960
	ds_read_b64_tr_b16 v[76:77], v202 offset:41472
	v_mfma_f32_32x32x16_bf16 v[50:65], v[174:177], v[190:193], v[50:65]
	v_sub_f32_e32 v78, v116, v0
	v_exp_f32_e32 v116, v78
	v_sub_f32_e32 v78, v117, v0
	v_exp_f32_e32 v117, v78
	ds_read_b64_tr_b16 v[78:79], v202 offset:45056
	ds_read_b64_tr_b16 v[80:81], v202 offset:45568
	v_mfma_f32_32x32x16_bf16 v[2:17], v[170:173], v[82:85], v[2:17]
	v_sub_f32_e32 v82, v118, v0
	v_exp_f32_e32 v118, v82
	v_sub_f32_e32 v82, v119, v0
	v_exp_f32_e32 v119, v82
	ds_read_b64_tr_b16 v[82:83], v202 offset:41984
	ds_read_b64_tr_b16 v[84:85], v202 offset:42496
	v_mfma_f32_32x32x16_bf16 v[50:65], v[170:173], v[86:89], v[50:65]
	v_sub_f32_e32 v86, v120, v0
	v_exp_f32_e32 v120, v86
	v_sub_f32_e32 v86, v121, v0
	v_exp_f32_e32 v121, v86
	ds_read_b64_tr_b16 v[86:87], v202 offset:46080
	ds_read_b64_tr_b16 v[88:89], v202 offset:46592
	s_waitcnt lgkmcnt(14)
	v_mfma_f32_32x32x16_bf16 v[2:17], v[166:169], v[90:93], v[2:17]
	v_sub_f32_e32 v90, v122, v0
	v_exp_f32_e32 v122, v90
	v_sub_f32_e32 v90, v123, v0
	v_exp_f32_e32 v123, v90
	ds_read_b64_tr_b16 v[90:91], v202 offset:43008
	ds_read_b64_tr_b16 v[92:93], v202 offset:43520
	s_waitcnt lgkmcnt(14)
	v_mfma_f32_32x32x16_bf16 v[50:65], v[166:169], v[94:97], v[50:65]
	v_sub_f32_e32 v94, v124, v0
	v_exp_f32_e32 v124, v94
	v_sub_f32_e32 v94, v125, v0
	v_exp_f32_e32 v125, v94
	ds_read_b64_tr_b16 v[94:95], v202 offset:47104
	ds_read_b64_tr_b16 v[96:97], v202 offset:47616
	s_waitcnt lgkmcnt(14)
	v_mfma_f32_32x32x16_bf16 v[2:17], v[162:165], v[70:73], v[2:17]
	v_sub_f32_e32 v70, v126, v0
	v_exp_f32_e32 v126, v70
	v_sub_f32_e32 v70, v127, v0
	v_exp_f32_e32 v127, v70
	ds_read_b64_tr_b16 v[178:179], v202 offset:44032
	ds_read_b64_tr_b16 v[180:181], v202 offset:44544
	s_waitcnt lgkmcnt(14)
	v_mfma_f32_32x32x16_bf16 v[50:65], v[162:165], v[66:69], v[50:65]
	v_sub_f32_e32 v66, v128, v0
	v_exp_f32_e32 v128, v66
	v_sub_f32_e32 v66, v129, v0
	v_exp_f32_e32 v129, v66
	ds_read_b64_tr_b16 v[186:187], v202 offset:48128
	ds_read_b64_tr_b16 v[188:189], v202 offset:48640
	s_waitcnt lgkmcnt(14)
	v_mfma_f32_32x32x16_bf16 v[34:49], v[174:177], v[74:77], v[34:49]
	v_sub_f32_e32 v66, v98, v0
	v_exp_f32_e32 v98, v66
	v_sub_f32_e32 v66, v99, v0
	v_exp_f32_e32 v99, v66
	s_waitcnt lgkmcnt(12)
	v_mfma_f32_32x32x16_bf16 v[18:33], v[174:177], v[78:81], v[18:33]
	v_sub_f32_e32 v66, v100, v0
	v_exp_f32_e32 v100, v66
	v_sub_f32_e32 v66, v101, v0
	v_exp_f32_e32 v101, v66
	s_waitcnt lgkmcnt(10)
	v_mfma_f32_32x32x16_bf16 v[34:49], v[170:173], v[82:85], v[34:49]
	v_sub_f32_e32 v66, v102, v0
	v_exp_f32_e32 v102, v66
	v_sub_f32_e32 v66, v103, v0
	v_exp_f32_e32 v103, v66
	s_waitcnt lgkmcnt(8)
	v_mfma_f32_32x32x16_bf16 v[18:33], v[170:173], v[86:89], v[18:33]
	v_sub_f32_e32 v66, v104, v0
	v_exp_f32_e32 v104, v66
	v_sub_f32_e32 v66, v105, v0
	v_exp_f32_e32 v105, v66
	v_add_u32_e32 v196, s12, v233
	ds_read_b128 v[66:69], v196
	s_waitcnt lgkmcnt(7)
	v_mfma_f32_32x32x16_bf16 v[34:49], v[166:169], v[90:93], v[34:49]
	v_sub_f32_e32 v70, v106, v0
	v_exp_f32_e32 v106, v70
	v_sub_f32_e32 v70, v107, v0
	v_exp_f32_e32 v107, v70
	ds_read_b128 v[70:73], v196 offset:512
	s_waitcnt lgkmcnt(6)
	v_mfma_f32_32x32x16_bf16 v[18:33], v[166:169], v[94:97], v[18:33]
	v_sub_f32_e32 v74, v108, v0
	v_exp_f32_e32 v108, v74
	v_sub_f32_e32 v74, v109, v0
	v_exp_f32_e32 v109, v74
	ds_read_b128 v[182:185], v196 offset:2048
	s_waitcnt lgkmcnt(5)
	v_mfma_f32_32x32x16_bf16 v[34:49], v[162:165], v[178:181], v[34:49]
	v_sub_f32_e32 v74, v110, v0
	v_exp_f32_e32 v110, v74
	v_sub_f32_e32 v74, v111, v0
	v_exp_f32_e32 v111, v74
	ds_read_b128 v[178:181], v196 offset:2560
	s_waitcnt lgkmcnt(4)
	v_mfma_f32_32x32x16_bf16 v[18:33], v[162:165], v[186:189], v[18:33]
	v_sub_f32_e32 v78, v112, v0
	v_exp_f32_e32 v112, v78
	v_sub_f32_e32 v78, v113, v0
	v_exp_f32_e32 v113, v78
	s_waitcnt vmcnt(3) lgkmcnt(4)
	s_barrier
	s_andn2_b64 vcc, exec, s[0:1]
	s_cbranch_vccnz .LBB0_321
	s_waitcnt lgkmcnt(0)
	s_mov_b32 s0, 0
	s_nop 0
	v_mbcnt_lo_u32_b32 v78, -1, s0
	v_mbcnt_hi_u32_b32 v78, -1, v78
	v_ashrrev_i32_e32 v78, 3, v78
	v_lshlrev_b32_e32 v78, 2, v78
	v_and_b32_e32 v78, -16, v78
	v_add_u32_e32 v90, s76, v78
	ds_read_b128 v[78:81], v90 offset:96
	ds_read_b128 v[82:85], v90 offset:64
	ds_read_b128 v[86:89], v90 offset:32
	ds_read_b128 v[90:93], v90
	s_waitcnt lgkmcnt(3)
	v_pk_mul_f32 v[14:15], v[14:15], v[78:79]
	s_waitcnt lgkmcnt(2)
	v_pk_mul_f32 v[10:11], v[10:11], v[82:83]
	s_waitcnt lgkmcnt(1)
	v_pk_mul_f32 v[6:7], v[6:7], v[86:87]
	v_pk_mul_f32 v[16:17], v[16:17], v[80:81]
	v_pk_mul_f32 v[12:13], v[12:13], v[84:85]
	v_pk_mul_f32 v[8:9], v[8:9], v[88:89]
	s_waitcnt lgkmcnt(0)
	v_pk_mul_f32 v[4:5], v[4:5], v[92:93]
	v_pk_mul_f32 v[2:3], v[2:3], v[90:91]
	v_pk_mul_f32 v[62:63], v[62:63], v[78:79]
	v_pk_mul_f32 v[58:59], v[58:59], v[82:83]
	v_pk_mul_f32 v[54:55], v[54:55], v[86:87]
	v_pk_mul_f32 v[64:65], v[64:65], v[80:81]
	v_pk_mul_f32 v[60:61], v[60:61], v[84:85]
	v_pk_mul_f32 v[56:57], v[56:57], v[88:89]
	v_pk_mul_f32 v[52:53], v[52:53], v[92:93]
	v_pk_mul_f32 v[50:51], v[50:51], v[90:91]
	v_pk_mul_f32 v[46:47], v[46:47], v[78:79]
	v_pk_mul_f32 v[42:43], v[42:43], v[82:83]
	v_pk_mul_f32 v[38:39], v[38:39], v[86:87]
	v_pk_mul_f32 v[48:49], v[48:49], v[80:81]
	v_pk_mul_f32 v[44:45], v[44:45], v[84:85]
	v_pk_mul_f32 v[40:41], v[40:41], v[88:89]
	v_pk_mul_f32 v[36:37], v[36:37], v[92:93]
	v_pk_mul_f32 v[34:35], v[34:35], v[90:91]
	v_pk_mul_f32 v[30:31], v[30:31], v[78:79]
	v_pk_mul_f32 v[26:27], v[26:27], v[82:83]
	v_pk_mul_f32 v[22:23], v[22:23], v[86:87]
	v_pk_mul_f32 v[32:33], v[32:33], v[80:81]
	v_pk_mul_f32 v[28:29], v[28:29], v[84:85]
	v_pk_mul_f32 v[24:25], v[24:25], v[88:89]
	v_pk_mul_f32 v[20:21], v[20:21], v[92:93]
	v_pk_mul_f32 v[18:19], v[18:19], v[90:91]
.LBB0_321:
	s_add_u32 s2, s46, 0x10000
	s_addc_u32 s3, s47, 0
	s_add_u32 s0, s44, 0x10000
	s_addc_u32 s1, s45, 0
	s_add_i32 s4, s5, 0x4000
	s_cmpk_lg_u32 s5, 0x8000
	s_cselect_b32 s11, s4, 0
	v_add_u32_e32 v195, s7, v234
	ds_read_b64_tr_b16 v[190:191], v195 offset:32768
	ds_read_b64_tr_b16 v[192:193], v195 offset:33280
	ds_read_b128 v[198:201], v196 offset:4096
	s_waitcnt lgkmcnt(6)
	v_mfma_f32_32x32x16_bf16 v[82:97], v[66:69], v[130:133], 0
	v_add_f32_e32 v78, v114, v115
	v_add_f32_e32 v78, v116, v78
	v_add_f32_e32 v78, v117, v78
	v_add_f32_e32 v78, v118, v78
	v_add_f32_e32 v78, v119, v78
	v_cvt_pk_bf16_f32 v174, v114, v115
	v_cvt_pk_bf16_f32 v175, v116, v117
	ds_read_b64_tr_b16 v[188:189], v195 offset:37376
	ds_read_b64_tr_b16 v[186:187], v195 offset:36864
	ds_read_b128 v[206:209], v196 offset:4608
	v_add_f32_e32 v66, v120, v78
	v_add_f32_e32 v66, v121, v66
	v_add_f32_e32 v66, v122, v66
	v_add_f32_e32 v162, v123, v66
	s_waitcnt lgkmcnt(8)
	v_mfma_f32_32x32x16_bf16 v[66:81], v[70:73], v[130:133], 0
	v_cvt_pk_bf16_f32 v176, v118, v119
	v_cvt_pk_bf16_f32 v177, v120, v121
	ds_read_b64_tr_b16 v[114:115], v195 offset:33792
	ds_read_b64_tr_b16 v[116:117], v195 offset:34304
	ds_read_b128 v[214:217], v196 offset:6144
	s_waitcnt lgkmcnt(10)
	v_mfma_f32_32x32x16_bf16 v[82:97], v[182:185], v[134:137], v[82:97]
	v_add_f32_e32 v118, v124, v162
	v_add_f32_e32 v118, v125, v118
	v_add_f32_e32 v118, v126, v118
	v_add_f32_e32 v162, v127, v118
	v_cvt_pk_bf16_f32 v170, v122, v123
	v_cvt_pk_bf16_f32 v171, v124, v125
	ds_read_b64_tr_b16 v[120:121], v195 offset:38400
	ds_read_b64_tr_b16 v[118:119], v195 offset:37888
	ds_read_b128 v[182:185], v196 offset:6656
	s_waitcnt lgkmcnt(12)
	v_mfma_f32_32x32x16_bf16 v[66:81], v[178:181], v[134:137], v[66:81]
	v_add_f32_e32 v122, v128, v162
	v_add_f32_e32 v122, v129, v122
	v_add_f32_e32 v122, v98, v122
	v_add_f32_e32 v162, v99, v122
	v_cvt_pk_bf16_f32 v172, v126, v127
	v_cvt_pk_bf16_f32 v173, v128, v129
	ds_read_b64_tr_b16 v[124:125], v195 offset:35328
	ds_read_b64_tr_b16 v[122:123], v195 offset:34816
	s_waitcnt lgkmcnt(11)
	v_mfma_f32_32x32x16_bf16 v[82:97], v[198:201], v[138:141], v[82:97]
	v_add_f32_e32 v126, v100, v162
	v_add_f32_e32 v126, v101, v126
	v_add_f32_e32 v126, v102, v126
	v_add_f32_e32 v162, v103, v126
	v_cvt_pk_bf16_f32 v166, v98, v99
	v_cvt_pk_bf16_f32 v167, v100, v101
	ds_read_b64_tr_b16 v[126:127], v195 offset:38912
	ds_read_b64_tr_b16 v[128:129], v195 offset:39424
	s_waitcnt lgkmcnt(10)
	v_mfma_f32_32x32x16_bf16 v[66:81], v[206:209], v[138:141], v[66:81]
	v_add_f32_e32 v98, v104, v162
	v_add_f32_e32 v98, v105, v98
	v_add_f32_e32 v98, v106, v98
	v_add_f32_e32 v98, v107, v98
	v_cvt_pk_bf16_f32 v168, v102, v103
	v_cvt_pk_bf16_f32 v169, v104, v105
	ds_read_b64_tr_b16 v[102:103], v195 offset:35840
	ds_read_b64_tr_b16 v[104:105], v195 offset:36352
	s_waitcnt lgkmcnt(9)
	v_mfma_f32_32x32x16_bf16 v[82:97], v[214:217], v[142:145], v[82:97]
	v_add_f32_e32 v98, v108, v98
	v_add_f32_e32 v98, v109, v98
	v_add_f32_e32 v98, v110, v98
	v_add_f32_e32 v196, v111, v98
	v_cvt_pk_bf16_f32 v162, v106, v107
	v_cvt_pk_bf16_f32 v163, v108, v109
	ds_read_b64_tr_b16 v[98:99], v195 offset:39936
	ds_read_b64_tr_b16 v[100:101], v195 offset:40448
	s_waitcnt lgkmcnt(8)
	v_mfma_f32_32x32x16_bf16 v[66:81], v[182:185], v[142:145], v[66:81]
	v_add_f32_e32 v106, v112, v196
	v_add_f32_e32 v106, v113, v106
	v_add_f32_e32 v106, 0, v106
	v_cvt_pk_bf16_f32 v164, v110, v111
	v_cvt_pk_bf16_f32 v165, v112, v113
	s_nop 0
	v_add_f32_e32 v214, v194, v106
	v_max_f32_e32 v106, v83, v83
	v_max_f32_e32 v107, v82, v82
	v_max_f32_e32 v106, v107, v106
	s_nop 1
	v_max3_f32 v107, v84, v85, v67
	v_max3_f32 v106, v106, v66, v68
	v_max3_f32 v106, v106, v69, v86
	v_max3_f32 v107, v107, v88, v89
	v_max3_f32 v106, v106, v87, v70
	v_max3_f32 v107, v107, v72, v73
	v_max3_f32 v106, v106, v71, v90
	v_max3_f32 v107, v107, v92, v93
	v_max3_f32 v106, v106, v91, v74
	v_max3_f32 v107, v107, v76, v77
	v_max3_f32 v106, v106, v75, v94
	v_max3_f32 v107, v107, v96, v97
	v_max3_f32 v106, v106, v95, v78
	v_max3_f32 v107, v107, v80, v81
	v_max3_f32 v106, v106, v79, v107
	s_add_i32 s4, s12, 0xffffe000
	v_mov_b32_e32 v107, v106
	s_cmp_lg_u32 s12, 0
	s_nop 0
	v_permlane32_swap_b32_e32 v106, v107
	s_cselect_b32 s4, s4, 0x6000
	v_max_f32_e32 v107, v107, v107
	v_max_f32_e32 v106, v106, v106
	s_add_i32 s4, s4, s71
	s_mov_b32 s7, m0
	s_mov_b32 m0, s4
	s_nop 3
	global_load_lds_dwordx4 v210, s[2:3]
	s_mov_b32 m0, s7
	v_max_f32_e32 v106, v106, v107
	s_add_i32 s2, s11, s72
	s_mov_b32 s3, m0
	s_mov_b32 m0, s2
	s_nop 3
	global_load_lds_dwordx4 v211, s[0:1]
	s_mov_b32 m0, s3
	v_sub_f32_e32 v106, v106, v0
	s_addk_i32 s2, 0x2000
	s_mov_b32 s3, m0
	s_mov_b32 m0, s2
	s_nop 3
	global_load_lds_dwordx4 v212, s[0:1]
	s_mov_b32 m0, s3
	v_cmp_lt_f32_e32 vcc, s87, v106
	s_cmp_lg_u64 vcc, 0
	s_cselect_b64 s[0:1], -1, 0
	s_cbranch_vccnz .LBB0_329
.LBB0_322:
	s_add_i32 s2, s12, 0x2000
	s_cmpk_lg_i32 s12, 0x6000
	s_cselect_b32 s15, s2, 0
	v_mfma_f32_32x32x16_bf16 v[2:17], v[174:177], v[190:193], v[2:17]
	v_sub_f32_e32 v82, v82, v0
	v_sub_f32_e32 v83, v83, v0
	v_exp_f32_e32 v82, v82
	v_exp_f32_e32 v83, v83
	ds_read_b64_tr_b16 v[106:107], v195 offset:40960
	ds_read_b64_tr_b16 v[108:109], v195 offset:41472
	v_mfma_f32_32x32x16_bf16 v[50:65], v[174:177], v[186:189], v[50:65]
	v_sub_f32_e32 v84, v84, v0
	v_sub_f32_e32 v85, v85, v0
	v_exp_f32_e32 v84, v84
	v_exp_f32_e32 v85, v85
	ds_read_b64_tr_b16 v[110:111], v195 offset:45056
	ds_read_b64_tr_b16 v[112:113], v195 offset:45568
	v_mfma_f32_32x32x16_bf16 v[2:17], v[170:173], v[114:117], v[2:17]
	v_sub_f32_e32 v86, v86, v0
	v_sub_f32_e32 v87, v87, v0
	v_exp_f32_e32 v86, v86
	v_exp_f32_e32 v87, v87
	ds_read_b64_tr_b16 v[114:115], v195 offset:41984
	ds_read_b64_tr_b16 v[116:117], v195 offset:42496
	v_mfma_f32_32x32x16_bf16 v[50:65], v[170:173], v[118:121], v[50:65]
	v_sub_f32_e32 v88, v88, v0
	v_sub_f32_e32 v89, v89, v0
	v_exp_f32_e32 v88, v88
	v_exp_f32_e32 v89, v89
	ds_read_b64_tr_b16 v[118:119], v195 offset:46080
	ds_read_b64_tr_b16 v[120:121], v195 offset:46592
	s_waitcnt lgkmcnt(14)
	v_mfma_f32_32x32x16_bf16 v[2:17], v[166:169], v[122:125], v[2:17]
	v_sub_f32_e32 v90, v90, v0
	v_sub_f32_e32 v91, v91, v0
	v_exp_f32_e32 v90, v90
	v_exp_f32_e32 v91, v91
	ds_read_b64_tr_b16 v[122:123], v195 offset:43008
	ds_read_b64_tr_b16 v[124:125], v195 offset:43520
	s_waitcnt lgkmcnt(14)
	v_mfma_f32_32x32x16_bf16 v[50:65], v[166:169], v[126:129], v[50:65]
	v_sub_f32_e32 v92, v92, v0
	v_sub_f32_e32 v93, v93, v0
	v_exp_f32_e32 v92, v92
	v_exp_f32_e32 v93, v93
	ds_read_b64_tr_b16 v[126:127], v195 offset:47104
	ds_read_b64_tr_b16 v[128:129], v195 offset:47616
	s_waitcnt lgkmcnt(14)
	v_mfma_f32_32x32x16_bf16 v[2:17], v[162:165], v[102:105], v[2:17]
	v_sub_f32_e32 v94, v94, v0
	v_sub_f32_e32 v95, v95, v0
	v_exp_f32_e32 v94, v94
	v_exp_f32_e32 v95, v95
	ds_read_b64_tr_b16 v[102:103], v195 offset:44032
	ds_read_b64_tr_b16 v[104:105], v195 offset:44544
	s_waitcnt lgkmcnt(14)
	v_mfma_f32_32x32x16_bf16 v[50:65], v[162:165], v[98:101], v[50:65]
	v_sub_f32_e32 v96, v96, v0
	v_sub_f32_e32 v97, v97, v0
	v_exp_f32_e32 v96, v96
	v_exp_f32_e32 v97, v97
	ds_read_b64_tr_b16 v[98:99], v195 offset:48128
	ds_read_b64_tr_b16 v[100:101], v195 offset:48640
	s_waitcnt lgkmcnt(14)
	v_mfma_f32_32x32x16_bf16 v[34:49], v[174:177], v[106:109], v[34:49]
	v_sub_f32_e32 v66, v66, v0
	v_sub_f32_e32 v67, v67, v0
	v_exp_f32_e32 v66, v66
	v_exp_f32_e32 v67, v67
	s_waitcnt lgkmcnt(12)
	v_mfma_f32_32x32x16_bf16 v[18:33], v[174:177], v[110:113], v[18:33]
	v_sub_f32_e32 v68, v68, v0
	v_sub_f32_e32 v69, v69, v0
	v_exp_f32_e32 v68, v68
	v_exp_f32_e32 v69, v69
	s_waitcnt lgkmcnt(10)
	v_mfma_f32_32x32x16_bf16 v[34:49], v[170:173], v[114:117], v[34:49]
	v_sub_f32_e32 v70, v70, v0
	v_sub_f32_e32 v71, v71, v0
	v_exp_f32_e32 v70, v70
	v_exp_f32_e32 v71, v71
	s_waitcnt lgkmcnt(8)
	v_mfma_f32_32x32x16_bf16 v[18:33], v[170:173], v[118:121], v[18:33]
	v_sub_f32_e32 v72, v72, v0
	v_sub_f32_e32 v73, v73, v0
	v_exp_f32_e32 v72, v72
	v_exp_f32_e32 v73, v73
	v_add_u32_e32 v106, s15, v233
	ds_read_b128 v[190:193], v106
	s_waitcnt lgkmcnt(7)
	v_mfma_f32_32x32x16_bf16 v[34:49], v[166:169], v[122:125], v[34:49]
	v_sub_f32_e32 v74, v74, v0
	v_sub_f32_e32 v75, v75, v0
	v_exp_f32_e32 v74, v74
	v_exp_f32_e32 v75, v75
	ds_read_b128 v[182:185], v106 offset:512
	s_waitcnt lgkmcnt(6)
	v_mfma_f32_32x32x16_bf16 v[18:33], v[166:169], v[126:129], v[18:33]
	v_sub_f32_e32 v76, v76, v0
	v_sub_f32_e32 v77, v77, v0
	v_exp_f32_e32 v76, v76
	v_exp_f32_e32 v77, v77
	ds_read_b128 v[186:189], v106 offset:2048
	s_waitcnt lgkmcnt(5)
	v_mfma_f32_32x32x16_bf16 v[34:49], v[162:165], v[102:105], v[34:49]
	v_sub_f32_e32 v78, v78, v0
	v_sub_f32_e32 v79, v79, v0
	v_exp_f32_e32 v78, v78
	v_exp_f32_e32 v79, v79
	ds_read_b128 v[178:181], v106 offset:2560
	s_waitcnt lgkmcnt(4)
	v_mfma_f32_32x32x16_bf16 v[18:33], v[162:165], v[98:101], v[18:33]
	v_sub_f32_e32 v80, v80, v0
	v_sub_f32_e32 v81, v81, v0
	v_exp_f32_e32 v80, v80
	v_exp_f32_e32 v81, v81
	s_waitcnt vmcnt(3) lgkmcnt(4)
	s_barrier
	s_andn2_b64 vcc, exec, s[0:1]
	s_cbranch_vccnz .LBB0_324
	s_waitcnt lgkmcnt(0)
	s_mov_b32 s0, 0
	s_nop 0
	v_mbcnt_lo_u32_b32 v98, -1, s0
	v_mbcnt_hi_u32_b32 v98, -1, v98
	v_ashrrev_i32_e32 v98, 3, v98
	v_lshlrev_b32_e32 v98, 2, v98
	v_and_b32_e32 v98, -16, v98
	v_add_u32_e32 v110, s76, v98
	ds_read_b128 v[98:101], v110 offset:96
	ds_read_b128 v[102:105], v110 offset:64
	ds_read_b128 v[106:109], v110 offset:32
	ds_read_b128 v[110:113], v110
	s_waitcnt lgkmcnt(3)
	v_pk_mul_f32 v[14:15], v[14:15], v[98:99]
	s_waitcnt lgkmcnt(2)
	v_pk_mul_f32 v[10:11], v[10:11], v[102:103]
	s_waitcnt lgkmcnt(1)
	v_pk_mul_f32 v[6:7], v[6:7], v[106:107]
	v_pk_mul_f32 v[16:17], v[16:17], v[100:101]
	v_pk_mul_f32 v[12:13], v[12:13], v[104:105]
	v_pk_mul_f32 v[8:9], v[8:9], v[108:109]
	s_waitcnt lgkmcnt(0)
	v_pk_mul_f32 v[4:5], v[4:5], v[112:113]
	v_pk_mul_f32 v[2:3], v[2:3], v[110:111]
	v_pk_mul_f32 v[62:63], v[62:63], v[98:99]
	v_pk_mul_f32 v[58:59], v[58:59], v[102:103]
	v_pk_mul_f32 v[54:55], v[54:55], v[106:107]
	v_pk_mul_f32 v[64:65], v[64:65], v[100:101]
	v_pk_mul_f32 v[60:61], v[60:61], v[104:105]
	v_pk_mul_f32 v[56:57], v[56:57], v[108:109]
	v_pk_mul_f32 v[52:53], v[52:53], v[112:113]
	v_pk_mul_f32 v[50:51], v[50:51], v[110:111]
	v_pk_mul_f32 v[46:47], v[46:47], v[98:99]
	v_pk_mul_f32 v[42:43], v[42:43], v[102:103]
	v_pk_mul_f32 v[38:39], v[38:39], v[106:107]
	v_pk_mul_f32 v[48:49], v[48:49], v[100:101]
	v_pk_mul_f32 v[44:45], v[44:45], v[104:105]
	v_pk_mul_f32 v[40:41], v[40:41], v[108:109]
	v_pk_mul_f32 v[36:37], v[36:37], v[112:113]
	v_pk_mul_f32 v[34:35], v[34:35], v[110:111]
	v_pk_mul_f32 v[30:31], v[30:31], v[98:99]
	v_pk_mul_f32 v[26:27], v[26:27], v[102:103]
	v_pk_mul_f32 v[22:23], v[22:23], v[106:107]
	v_pk_mul_f32 v[32:33], v[32:33], v[100:101]
	v_pk_mul_f32 v[28:29], v[28:29], v[104:105]
	v_pk_mul_f32 v[24:25], v[24:25], v[108:109]
	v_pk_mul_f32 v[20:21], v[20:21], v[112:113]
	v_pk_mul_f32 v[18:19], v[18:19], v[110:111]

.LBB0_332:
	s_waitcnt lgkmcnt(0)
	s_add_i32 s1, s0, 3
	s_cmp_ge_u32 s1, s73
	s_cbranch_scc1 .LBB0_382
	s_add_i32 s14, s0, 2
.LBB0_334:
	v_add_u32_e32 v202, s5, v234
	v_add_u32_e32 v162, s15, v233
	ds_read_b64_tr_b16 v[200:201], v202 offset:33280
	ds_read_b128 v[204:207], v162 offset:4096
	ds_read_b64_tr_b16 v[198:199], v202 offset:32768
	s_waitcnt lgkmcnt(3)
	v_mfma_f32_32x32x16_bf16 v[114:129], v[190:193], v[130:133], 0
	v_add_f32_e32 v98, v82, v83
	v_add_f32_e32 v98, v84, v98
	v_add_f32_e32 v98, v85, v98
	v_add_f32_e32 v98, v86, v98
	v_add_f32_e32 v98, v87, v98
	v_cvt_pk_bf16_f32 v174, v82, v83
	v_cvt_pk_bf16_f32 v175, v84, v85
	ds_read_b64_tr_b16 v[190:191], v202 offset:36864
	ds_read_b64_tr_b16 v[192:193], v202 offset:37376
	ds_read_b128 v[236:239], v162 offset:4608
	v_add_f32_e32 v82, v88, v98
	v_mfma_f32_32x32x16_bf16 v[98:113], v[182:185], v[130:133], 0
	v_add_f32_e32 v82, v89, v82
	v_add_f32_e32 v82, v90, v82
	v_add_f32_e32 v163, v91, v82
	v_cvt_pk_bf16_f32 v176, v86, v87
	v_cvt_pk_bf16_f32 v177, v88, v89
	ds_read_b64_tr_b16 v[84:85], v202 offset:34304
	ds_read_b128 v[182:185], v162 offset:6144
	ds_read_b64_tr_b16 v[82:83], v202 offset:33792
	s_waitcnt lgkmcnt(6)
	v_mfma_f32_32x32x16_bf16 v[114:129], v[186:189], v[134:137], v[114:129]
	v_add_f32_e32 v86, v92, v163
	v_add_f32_e32 v86, v93, v86
	v_add_f32_e32 v86, v94, v86
	v_add_f32_e32 v163, v95, v86
	v_cvt_pk_bf16_f32 v170, v90, v91
	v_cvt_pk_bf16_f32 v171, v92, v93
	ds_read_b64_tr_b16 v[86:87], v202 offset:37888
	ds_read_b64_tr_b16 v[88:89], v202 offset:38400
	ds_read_b128 v[186:189], v162 offset:6656
	v_mfma_f32_32x32x16_bf16 v[98:113], v[178:181], v[134:137], v[98:113]
	v_add_f32_e32 v90, v96, v163
	v_add_f32_e32 v90, v97, v90
	v_add_f32_e32 v90, v66, v90
	v_add_f32_e32 v162, v67, v90
	v_cvt_pk_bf16_f32 v172, v94, v95
	v_cvt_pk_bf16_f32 v173, v96, v97
	ds_read_b64_tr_b16 v[92:93], v202 offset:35328
	ds_read_b64_tr_b16 v[90:91], v202 offset:34816
	s_waitcnt lgkmcnt(5)
	v_mfma_f32_32x32x16_bf16 v[114:129], v[204:207], v[138:141], v[114:129]
	v_add_f32_e32 v94, v68, v162
	v_add_f32_e32 v94, v69, v94
	v_add_f32_e32 v94, v70, v94
	v_add_f32_e32 v162, v71, v94
	v_cvt_pk_bf16_f32 v166, v66, v67
	v_cvt_pk_bf16_f32 v167, v68, v69
	ds_read_b64_tr_b16 v[94:95], v202 offset:38912
	ds_read_b64_tr_b16 v[96:97], v202 offset:39424
	v_mfma_f32_32x32x16_bf16 v[98:113], v[236:239], v[138:141], v[98:113]
	v_add_f32_e32 v66, v72, v162
	v_add_f32_e32 v66, v73, v66
	v_add_f32_e32 v66, v74, v66
	v_add_f32_e32 v66, v75, v66
	v_cvt_pk_bf16_f32 v168, v70, v71
	v_cvt_pk_bf16_f32 v169, v72, v73
	ds_read_b64_tr_b16 v[70:71], v202 offset:35840
	ds_read_b64_tr_b16 v[72:73], v202 offset:36352
	s_waitcnt lgkmcnt(4)
	v_mfma_f32_32x32x16_bf16 v[114:129], v[182:185], v[142:145], v[114:129]
	v_add_f32_e32 v66, v76, v66
	v_add_f32_e32 v66, v77, v66
	v_add_f32_e32 v66, v78, v66
	v_add_f32_e32 v182, v79, v66
	v_cvt_pk_bf16_f32 v162, v74, v75
	v_cvt_pk_bf16_f32 v163, v76, v77
	ds_read_b64_tr_b16 v[66:67], v202 offset:39936
	ds_read_b64_tr_b16 v[68:69], v202 offset:40448
	v_mfma_f32_32x32x16_bf16 v[98:113], v[186:189], v[142:145], v[98:113]
	v_add_f32_e32 v74, v80, v182
	v_add_f32_e32 v74, v81, v74
	v_add_f32_e32 v74, 0, v74
	v_cvt_pk_bf16_f32 v164, v78, v79
	v_cvt_pk_bf16_f32 v165, v80, v81
	s_add_i32 s0, s8, 1
	s_cmp_ge_u32 s0, s73
	s_cselect_b64 s[0:1], -1, 0
	s_and_b64 vcc, exec, s[0:1]
	s_cbranch_vccnz .LBB0_336
	s_add_u32 s2, s46, 0x10000
	s_addc_u32 s3, s47, 0
	s_add_i32 s4, s15, 0xffffe000
	s_cmp_lg_u32 s15, 0
	s_cselect_b32 s4, s4, 0x6000
	s_add_i32 s4, s4, s71
	s_mov_b32 s5, m0
	s_mov_b32 m0, s4
	s_nop 3
	global_load_lds_dwordx4 v210, s[46:47]
	s_mov_b32 m0, s5
	s_mov_b64 s[46:47], s[2:3]

.LBB0_339:
	v_mfma_f32_32x32x16_bf16 v[2:17], v[174:177], v[198:201], v[2:17]
	v_sub_f32_e32 v74, v114, v0
	v_exp_f32_e32 v114, v74
	v_sub_f32_e32 v74, v115, v0
	v_exp_f32_e32 v115, v74
	ds_read_b64_tr_b16 v[74:75], v202 offset:40960
	ds_read_b64_tr_b16 v[76:77], v202 offset:41472
	v_mfma_f32_32x32x16_bf16 v[50:65], v[174:177], v[190:193], v[50:65]
	v_sub_f32_e32 v78, v116, v0
	v_exp_f32_e32 v116, v78
	v_sub_f32_e32 v78, v117, v0
	v_exp_f32_e32 v117, v78
	ds_read_b64_tr_b16 v[78:79], v202 offset:45056
	ds_read_b64_tr_b16 v[80:81], v202 offset:45568
	v_mfma_f32_32x32x16_bf16 v[2:17], v[170:173], v[82:85], v[2:17]
	v_sub_f32_e32 v82, v118, v0
	v_exp_f32_e32 v118, v82
	v_sub_f32_e32 v82, v119, v0
	v_exp_f32_e32 v119, v82
	ds_read_b64_tr_b16 v[82:83], v202 offset:41984
	ds_read_b64_tr_b16 v[84:85], v202 offset:42496
	v_mfma_f32_32x32x16_bf16 v[50:65], v[170:173], v[86:89], v[50:65]
	v_sub_f32_e32 v86, v120, v0
	v_exp_f32_e32 v120, v86
	v_sub_f32_e32 v86, v121, v0
	v_exp_f32_e32 v121, v86
	ds_read_b64_tr_b16 v[86:87], v202 offset:46080
	ds_read_b64_tr_b16 v[88:89], v202 offset:46592
	v_mfma_f32_32x32x16_bf16 v[2:17], v[166:169], v[90:93], v[2:17]
	v_sub_f32_e32 v90, v122, v0
	v_exp_f32_e32 v122, v90
	v_sub_f32_e32 v90, v123, v0
	v_exp_f32_e32 v123, v90
	ds_read_b64_tr_b16 v[90:91], v202 offset:43008
	ds_read_b64_tr_b16 v[92:93], v202 offset:43520
	s_waitcnt lgkmcnt(14)
	v_mfma_f32_32x32x16_bf16 v[50:65], v[166:169], v[94:97], v[50:65]
	v_sub_f32_e32 v94, v124, v0
	v_exp_f32_e32 v124, v94
	v_sub_f32_e32 v94, v125, v0
	v_exp_f32_e32 v125, v94
	ds_read_b64_tr_b16 v[94:95], v202 offset:47104
	ds_read_b64_tr_b16 v[96:97], v202 offset:47616
	s_waitcnt lgkmcnt(14)
	v_mfma_f32_32x32x16_bf16 v[2:17], v[162:165], v[70:73], v[2:17]
	v_sub_f32_e32 v70, v126, v0
	v_exp_f32_e32 v126, v70
	v_sub_f32_e32 v70, v127, v0
	v_exp_f32_e32 v127, v70
	ds_read_b64_tr_b16 v[70:71], v202 offset:44032
	ds_read_b64_tr_b16 v[72:73], v202 offset:44544
	s_waitcnt lgkmcnt(14)
	v_mfma_f32_32x32x16_bf16 v[50:65], v[162:165], v[66:69], v[50:65]
	v_sub_f32_e32 v66, v128, v0
	v_exp_f32_e32 v128, v66
	v_sub_f32_e32 v66, v129, v0
	v_exp_f32_e32 v129, v66
	ds_read_b64_tr_b16 v[194:195], v202 offset:48128
	ds_read_b64_tr_b16 v[196:197], v202 offset:48640
	s_waitcnt lgkmcnt(14)
	v_mfma_f32_32x32x16_bf16 v[34:49], v[174:177], v[74:77], v[34:49]
	v_sub_f32_e32 v66, v98, v0
	v_exp_f32_e32 v98, v66
	v_sub_f32_e32 v66, v99, v0
	v_exp_f32_e32 v99, v66
	s_waitcnt lgkmcnt(12)
	v_mfma_f32_32x32x16_bf16 v[18:33], v[174:177], v[78:81], v[18:33]
	v_sub_f32_e32 v66, v100, v0
	v_exp_f32_e32 v100, v66
	v_sub_f32_e32 v66, v101, v0
	v_exp_f32_e32 v101, v66
	s_waitcnt lgkmcnt(10)
	v_mfma_f32_32x32x16_bf16 v[34:49], v[170:173], v[82:85], v[34:49]
	v_sub_f32_e32 v66, v102, v0
	v_exp_f32_e32 v102, v66
	v_sub_f32_e32 v66, v103, v0
	v_exp_f32_e32 v103, v66
	s_waitcnt lgkmcnt(8)
	v_mfma_f32_32x32x16_bf16 v[18:33], v[170:173], v[86:89], v[18:33]
	v_sub_f32_e32 v66, v104, v0
	v_exp_f32_e32 v104, v66
	v_sub_f32_e32 v66, v105, v0
	v_exp_f32_e32 v105, v66
	v_add_u32_e32 v216, s12, v233
	ds_read_b128 v[190:193], v216
	s_waitcnt lgkmcnt(7)
	v_mfma_f32_32x32x16_bf16 v[34:49], v[166:169], v[90:93], v[34:49]
	v_sub_f32_e32 v66, v106, v0
	v_exp_f32_e32 v106, v66
	v_sub_f32_e32 v66, v107, v0
	v_exp_f32_e32 v107, v66
	ds_read_b128 v[182:185], v216 offset:512
	s_waitcnt lgkmcnt(6)
	v_mfma_f32_32x32x16_bf16 v[18:33], v[166:169], v[94:97], v[18:33]
	v_sub_f32_e32 v66, v108, v0
	v_exp_f32_e32 v108, v66
	v_sub_f32_e32 v66, v109, v0
	v_exp_f32_e32 v109, v66
	ds_read_b128 v[186:189], v216 offset:2048
	s_waitcnt lgkmcnt(5)
	v_mfma_f32_32x32x16_bf16 v[34:49], v[162:165], v[70:73], v[34:49]
	v_sub_f32_e32 v66, v110, v0
	v_exp_f32_e32 v110, v66
	v_sub_f32_e32 v66, v111, v0
	v_exp_f32_e32 v111, v66
	ds_read_b128 v[178:181], v216 offset:2560
	s_waitcnt lgkmcnt(4)
	v_mfma_f32_32x32x16_bf16 v[18:33], v[162:165], v[194:197], v[18:33]
	v_sub_f32_e32 v70, v112, v0
	v_exp_f32_e32 v112, v70
	v_sub_f32_e32 v70, v113, v0
	v_exp_f32_e32 v113, v70
	s_mov_b64 s[4:5], -1
	s_and_b64 vcc, exec, s[0:1]
	s_cbranch_vccnz .LBB0_347
	s_andn2_b64 vcc, exec, s[4:5]
	s_cbranch_vccz .LBB0_352

.LBB0_343:
	v_add_u32_e32 v215, s11, v234
	ds_read_b64_tr_b16 v[206:207], v215 offset:32768
	ds_read_b64_tr_b16 v[208:209], v215 offset:33280
	ds_read_b128 v[236:239], v216 offset:4096
	s_waitcnt lgkmcnt(3)
	v_mfma_f32_32x32x16_bf16 v[82:97], v[190:193], v[130:133], 0
	v_add_f32_e32 v70, v114, v115
	v_add_f32_e32 v70, v116, v70
	v_add_f32_e32 v70, v117, v70
	v_add_f32_e32 v70, v118, v70
	v_add_f32_e32 v70, v119, v70
	v_cvt_pk_bf16_f32 v174, v114, v115
	v_cvt_pk_bf16_f32 v175, v116, v117
	ds_read_b64_tr_b16 v[204:205], v215 offset:37376
	ds_read_b64_tr_b16 v[202:203], v215 offset:36864
	ds_read_b128 v[246:249], v216 offset:4608
	v_add_f32_e32 v70, v120, v70
	v_add_f32_e32 v70, v121, v70
	v_add_f32_e32 v70, v122, v70
	v_add_f32_e32 v114, v123, v70
	v_mfma_f32_32x32x16_bf16 v[66:81], v[182:185], v[130:133], 0
	v_cvt_pk_bf16_f32 v176, v118, v119
	v_cvt_pk_bf16_f32 v177, v120, v121
	ds_read_b64_tr_b16 v[198:199], v215 offset:33792
	ds_read_b64_tr_b16 v[200:201], v215 offset:34304
	ds_read_b128 v[226:229], v216 offset:6144
	s_waitcnt lgkmcnt(6)
	v_mfma_f32_32x32x16_bf16 v[82:97], v[186:189], v[134:137], v[82:97]
	v_add_f32_e32 v114, v124, v114
	v_add_f32_e32 v114, v125, v114
	v_add_f32_e32 v114, v126, v114
	v_add_f32_e32 v118, v127, v114
	v_cvt_pk_bf16_f32 v170, v122, v123
	v_cvt_pk_bf16_f32 v171, v124, v125
	ds_read_b64_tr_b16 v[116:117], v215 offset:38400
	ds_read_b64_tr_b16 v[114:115], v215 offset:37888
	ds_read_b128 v[216:219], v216 offset:6656
	v_mfma_f32_32x32x16_bf16 v[66:81], v[178:181], v[134:137], v[66:81]
	v_add_f32_e32 v118, v128, v118
	v_add_f32_e32 v118, v129, v118
	v_add_f32_e32 v118, v98, v118
	v_add_f32_e32 v122, v99, v118
	v_cvt_pk_bf16_f32 v172, v126, v127
	v_cvt_pk_bf16_f32 v173, v128, v129
	ds_read_b64_tr_b16 v[120:121], v215 offset:35328
	ds_read_b64_tr_b16 v[118:119], v215 offset:34816
	s_waitcnt lgkmcnt(5)
	v_mfma_f32_32x32x16_bf16 v[82:97], v[236:239], v[138:141], v[82:97]
	v_add_f32_e32 v122, v100, v122
	v_add_f32_e32 v122, v101, v122
	v_add_f32_e32 v122, v102, v122
	v_add_f32_e32 v162, v103, v122
	v_cvt_pk_bf16_f32 v166, v98, v99
	v_cvt_pk_bf16_f32 v167, v100, v101
	ds_read_b64_tr_b16 v[122:123], v215 offset:38912
	ds_read_b64_tr_b16 v[124:125], v215 offset:39424
	v_mfma_f32_32x32x16_bf16 v[66:81], v[246:249], v[138:141], v[66:81]
	v_add_f32_e32 v98, v104, v162
	v_add_f32_e32 v98, v105, v98
	v_add_f32_e32 v98, v106, v98
	v_add_f32_e32 v98, v107, v98
	v_cvt_pk_bf16_f32 v168, v102, v103
	v_cvt_pk_bf16_f32 v169, v104, v105
	ds_read_b64_tr_b16 v[102:103], v215 offset:35840
	ds_read_b64_tr_b16 v[104:105], v215 offset:36352
	s_waitcnt lgkmcnt(4)
	v_mfma_f32_32x32x16_bf16 v[82:97], v[226:229], v[142:145], v[82:97]
	v_add_f32_e32 v98, v108, v98
	v_add_f32_e32 v98, v109, v98
	v_add_f32_e32 v98, v110, v98
	v_add_f32_e32 v226, v111, v98
	v_cvt_pk_bf16_f32 v162, v106, v107
	v_cvt_pk_bf16_f32 v163, v108, v109
	ds_read_b64_tr_b16 v[98:99], v215 offset:39936
	ds_read_b64_tr_b16 v[100:101], v215 offset:40448
	v_mfma_f32_32x32x16_bf16 v[66:81], v[216:219], v[142:145], v[66:81]
	v_add_f32_e32 v106, v112, v226
	v_add_f32_e32 v106, v113, v106
	v_add_f32_e32 v106, 0, v106
	v_cvt_pk_bf16_f32 v164, v110, v111
	v_cvt_pk_bf16_f32 v165, v112, v113
	s_add_i32 s16, s8, 2
	s_cmp_ge_u32 s16, s73
	s_cselect_b64 s[2:3], -1, 0
	s_and_b64 vcc, exec, s[2:3]
	s_cbranch_vccnz .LBB0_345
	s_add_u32 s4, s46, 0x10000
	s_addc_u32 s5, s47, 0
	s_add_i32 s6, s12, 0xffffe000
	s_cmp_lg_u32 s12, 0
	s_cselect_b32 s6, s6, 0x6000
	s_add_i32 s6, s6, s71
	s_mov_b32 s7, m0
	s_mov_b32 m0, s6
	s_nop 3
	global_load_lds_dwordx4 v210, s[46:47]
	s_mov_b32 m0, s7
	s_mov_b64 s[46:47], s[4:5]

.LBB0_362:
	s_waitcnt lgkmcnt(2)
	v_mfma_f32_32x32x16_bf16 v[34:49], v[162:165], v[102:105], v[34:49]
	v_sub_f32_e32 v78, v78, v0
	v_sub_f32_e32 v79, v79, v0
	v_exp_f32_e32 v78, v78
	v_exp_f32_e32 v79, v79
	s_and_b64 vcc, exec, s[4:5]
	s_cbranch_vccnz .LBB0_364
	ds_read_b128 v[178:181], v114 offset:2560
.LBB0_364:
	s_waitcnt lgkmcnt(0)
	v_mfma_f32_32x32x16_bf16 v[18:33], v[162:165], v[98:101], v[18:33]
	v_sub_f32_e32 v80, v80, v0
	v_sub_f32_e32 v81, v81, v0
	v_exp_f32_e32 v80, v80
	v_exp_f32_e32 v81, v81
	s_mov_b64 s[4:5], -1
	s_and_b64 vcc, exec, s[2:3]
	s_cbranch_vccnz .LBB0_370
	s_andn2_b64 vcc, exec, s[4:5]
	s_cbranch_vccz .LBB0_375

.LBB0_383:
	v_add_u32_e32 v215, s13, v234
	v_add_u32_e32 v162, s15, v233
	ds_read_b64_tr_b16 v[208:209], v215 offset:33280
	ds_read_b128 v[198:201], v162 offset:4096
	ds_read_b64_tr_b16 v[206:207], v215 offset:32768
	v_add_f32_e32 v98, v82, v83
	v_add_f32_e32 v98, v84, v98
	v_add_f32_e32 v98, v85, v98
	v_add_f32_e32 v98, v86, v98
	v_add_f32_e32 v114, v87, v98
	s_waitcnt lgkmcnt(3)
	v_mfma_f32_32x32x16_bf16 v[98:113], v[190:193], v[130:133], 0
	v_cvt_pk_bf16_f32 v174, v82, v83
	v_cvt_pk_bf16_f32 v175, v84, v85
	ds_read_b64_tr_b16 v[202:203], v215 offset:36864
	ds_read_b64_tr_b16 v[204:205], v215 offset:37376
	ds_read_b128 v[82:85], v162 offset:4608
	v_add_f32_e32 v114, v88, v114
	v_add_f32_e32 v114, v89, v114
	v_add_f32_e32 v114, v90, v114
	v_add_f32_e32 v163, v91, v114
	v_cvt_pk_bf16_f32 v176, v86, v87
	v_cvt_pk_bf16_f32 v177, v88, v89
	v_mfma_f32_32x32x16_bf16 v[114:129], v[182:185], v[130:133], 0
	ds_read_b64_tr_b16 v[184:185], v215 offset:34304
	ds_read_b128 v[86:89], v162 offset:6144
	ds_read_b64_tr_b16 v[182:183], v215 offset:33792
	s_waitcnt lgkmcnt(6)
	v_mfma_f32_32x32x16_bf16 v[98:113], v[186:189], v[134:137], v[98:113]
	v_add_f32_e32 v163, v92, v163
	v_add_f32_e32 v163, v93, v163
	v_add_f32_e32 v163, v94, v163
	v_add_f32_e32 v163, v95, v163
	v_cvt_pk_bf16_f32 v170, v90, v91
	v_cvt_pk_bf16_f32 v171, v92, v93
	ds_read_b64_tr_b16 v[186:187], v215 offset:37888
	ds_read_b64_tr_b16 v[188:189], v215 offset:38400
	ds_read_b128 v[90:93], v162 offset:6656
	v_add_f32_e32 v162, v96, v163
	v_add_f32_e32 v162, v97, v162
	v_add_f32_e32 v162, v66, v162
	v_add_f32_e32 v162, v67, v162
	v_cvt_pk_bf16_f32 v172, v94, v95
	v_cvt_pk_bf16_f32 v173, v96, v97
	v_mfma_f32_32x32x16_bf16 v[114:129], v[178:181], v[134:137], v[114:129]
	ds_read_b64_tr_b16 v[180:181], v215 offset:35328
	ds_read_b64_tr_b16 v[178:179], v215 offset:34816
	s_waitcnt lgkmcnt(5)
	v_mfma_f32_32x32x16_bf16 v[98:113], v[198:201], v[138:141], v[98:113]
	v_add_f32_e32 v162, v68, v162
	v_add_f32_e32 v162, v69, v162
	v_add_f32_e32 v162, v70, v162
	v_add_f32_e32 v162, v71, v162
	v_cvt_pk_bf16_f32 v166, v66, v67
	v_cvt_pk_bf16_f32 v167, v68, v69
	ds_read_b64_tr_b16 v[198:199], v215 offset:38912
	ds_read_b64_tr_b16 v[200:201], v215 offset:39424
	v_add_f32_e32 v66, v72, v162
	v_add_f32_e32 v66, v73, v66
	v_add_f32_e32 v66, v74, v66
	v_add_f32_e32 v66, v75, v66
	v_cvt_pk_bf16_f32 v168, v70, v71
	v_cvt_pk_bf16_f32 v169, v72, v73
	v_mfma_f32_32x32x16_bf16 v[114:129], v[82:85], v[138:141], v[114:129]
	ds_read_b64_tr_b16 v[194:195], v215 offset:35840
	ds_read_b64_tr_b16 v[196:197], v215 offset:36352
	s_waitcnt lgkmcnt(4)
	v_mfma_f32_32x32x16_bf16 v[98:113], v[86:89], v[142:145], v[98:113]
	v_add_f32_e32 v66, v76, v66
	v_add_f32_e32 v66, v77, v66
	v_add_f32_e32 v66, v78, v66
	v_add_f32_e32 v66, v79, v66
	v_cvt_pk_bf16_f32 v162, v74, v75
	v_cvt_pk_bf16_f32 v163, v76, v77
	ds_read_b64_tr_b16 v[190:191], v215 offset:39936
	ds_read_b64_tr_b16 v[192:193], v215 offset:40448
	v_add_f32_e32 v66, v80, v66
	v_add_f32_e32 v66, v81, v66
	v_add_f32_e32 v66, 0, v66
	v_cvt_pk_bf16_f32 v164, v78, v79
	v_cvt_pk_bf16_f32 v165, v80, v81
	v_mfma_f32_32x32x16_bf16 v[114:129], v[90:93], v[142:145], v[114:129]
	s_nop 0
	v_add_f32_e32 v213, v214, v66
	s_mov_b32 s0, 0
	s_nop 0
	v_mbcnt_lo_u32_b32 v66, -1, s0
	v_mbcnt_hi_u32_b32 v66, -1, v66
	v_and_or_b32 v81, v66, 31, s75
	v_ashrrev_i32_e32 v66, 5, v66
	s_nop 0
	v_lshlrev_b32_e32 v214, 2, v66
	v_add_u32_e32 v66, 0xe0, v214
	v_add_u32_e32 v67, 0xc0, v214
	v_cmp_le_i32_e32 vcc, v66, v81
	v_add_u32_e32 v68, 0xc2, v214
	v_add_u32_e32 v69, 0xc3, v214
	v_cndmask_b32_e32 v66, v250, v114, vcc
	v_cmp_lt_i32_e32 vcc, v67, v81
	v_add_u32_e32 v70, 0xc8, v214
	v_add_u32_e32 v71, 0xc9, v214
	v_cndmask_b32_e32 v83, v250, v99, vcc
	v_cmp_le_i32_e32 vcc, v67, v81
	v_add_u32_e32 v67, 0xe1, v214
	v_add_u32_e32 v72, 0xca, v214
	v_cndmask_b32_e32 v82, v250, v98, vcc
	v_cmp_le_i32_e32 vcc, v67, v81
	v_add_u32_e32 v73, 0xcb, v214
	v_add_u32_e32 v74, 0xd0, v214
	v_cndmask_b32_e32 v67, v250, v115, vcc
	v_cmp_le_i32_e32 vcc, v68, v81
	v_add_u32_e32 v68, 0xe2, v214
	v_add_u32_e32 v75, 0xd1, v214
	v_cndmask_b32_e32 v84, v250, v100, vcc
	v_cmp_le_i32_e32 vcc, v68, v81
	v_add_u32_e32 v76, 0xd2, v214
	v_add_u32_e32 v77, 0xd3, v214
	v_cndmask_b32_e32 v68, v250, v116, vcc
	v_cmp_le_i32_e32 vcc, v69, v81
	v_add_u32_e32 v69, 0xe3, v214
	v_add_u32_e32 v78, 0xd8, v214
	v_cndmask_b32_e32 v85, v250, v101, vcc
	v_cmp_le_i32_e32 vcc, v69, v81
	v_add_u32_e32 v79, 0xd9, v214
	v_add_u32_e32 v80, 0xda, v214
	v_cndmask_b32_e32 v69, v250, v117, vcc
	v_cmp_le_i32_e32 vcc, v70, v81
	v_add_u32_e32 v70, 0xe8, v214
	v_add_u32_e32 v97, 0xdb, v214
	v_cndmask_b32_e32 v86, v250, v102, vcc
	v_cmp_le_i32_e32 vcc, v70, v81
	v_add_u32_e32 v98, 0xfb, v214
	v_max_f32_e32 v99, v82, v82
	v_cndmask_b32_e32 v70, v250, v118, vcc
	v_cmp_le_i32_e32 vcc, v71, v81
	v_add_u32_e32 v71, 0xe9, v214
	s_nop 0
	v_cndmask_b32_e32 v87, v250, v103, vcc
	v_cmp_le_i32_e32 vcc, v71, v81
	s_nop 1
	v_cndmask_b32_e32 v71, v250, v119, vcc
	v_cmp_le_i32_e32 vcc, v72, v81
	v_add_u32_e32 v72, 0xea, v214
	s_nop 0
	v_cndmask_b32_e32 v88, v250, v104, vcc
	v_cmp_le_i32_e32 vcc, v72, v81
	s_nop 1
	v_cndmask_b32_e32 v72, v250, v120, vcc
	v_cmp_le_i32_e32 vcc, v73, v81
	v_add_u32_e32 v73, 0xeb, v214
	s_nop 0
	v_cndmask_b32_e32 v89, v250, v105, vcc
	v_cmp_le_i32_e32 vcc, v73, v81
	s_nop 1
	v_cndmask_b32_e32 v73, v250, v121, vcc
	v_cmp_le_i32_e32 vcc, v74, v81
	v_add_u32_e32 v74, 0xf0, v214
	s_nop 0
	v_cndmask_b32_e32 v90, v250, v106, vcc
	v_cmp_le_i32_e32 vcc, v74, v81
	s_nop 1
	v_cndmask_b32_e32 v74, v250, v122, vcc
	v_cmp_le_i32_e32 vcc, v75, v81
	v_add_u32_e32 v75, 0xf1, v214
	s_nop 0
	v_cndmask_b32_e32 v91, v250, v107, vcc
	v_cmp_le_i32_e32 vcc, v75, v81
	s_nop 1
	v_cndmask_b32_e32 v75, v250, v123, vcc
	v_cmp_le_i32_e32 vcc, v76, v81
	v_add_u32_e32 v76, 0xf2, v214
	s_nop 0
	v_cndmask_b32_e32 v92, v250, v108, vcc
	v_cmp_le_i32_e32 vcc, v76, v81
	s_nop 1
	v_cndmask_b32_e32 v76, v250, v124, vcc
	v_cmp_le_i32_e32 vcc, v77, v81
	v_add_u32_e32 v77, 0xf3, v214
	s_nop 0
	v_cndmask_b32_e32 v93, v250, v109, vcc
	v_cmp_le_i32_e32 vcc, v77, v81
	s_nop 1
	v_cndmask_b32_e32 v77, v250, v125, vcc
	v_cmp_le_i32_e32 vcc, v78, v81
	v_add_u32_e32 v78, 0xf8, v214
	s_nop 0
	v_cndmask_b32_e32 v94, v250, v110, vcc
	v_cmp_le_i32_e32 vcc, v78, v81
	s_nop 1
	v_cndmask_b32_e32 v78, v250, v126, vcc
	v_cmp_le_i32_e32 vcc, v79, v81
	v_add_u32_e32 v79, 0xf9, v214
	s_nop 0
	v_cndmask_b32_e32 v95, v250, v111, vcc
	v_cmp_le_i32_e32 vcc, v79, v81
	s_nop 1
	v_cndmask_b32_e32 v79, v250, v127, vcc
	v_cmp_le_i32_e32 vcc, v80, v81
	v_add_u32_e32 v80, 0xfa, v214
	s_nop 0
	v_cndmask_b32_e32 v96, v250, v112, vcc
	v_cmp_le_i32_e32 vcc, v80, v81
	s_nop 1
	v_cndmask_b32_e32 v80, v250, v128, vcc
	v_cmp_le_i32_e32 vcc, v97, v81
	s_nop 1
	v_cndmask_b32_e32 v97, v250, v113, vcc
	v_cmp_le_i32_e32 vcc, v98, v81
	v_max_f32_e32 v98, v83, v83
	v_max_f32_e32 v98, v99, v98
	v_max3_f32 v99, v84, v85, v67
	v_max3_f32 v98, v98, v66, v68
	v_max3_f32 v98, v98, v69, v86
	v_max3_f32 v99, v99, v88, v89
	v_max3_f32 v98, v98, v87, v70
	v_max3_f32 v99, v99, v72, v73
	v_max3_f32 v98, v98, v71, v90
	v_max3_f32 v99, v99, v92, v93
	v_max3_f32 v98, v98, v91, v74
	v_max3_f32 v99, v99, v76, v77
	v_cndmask_b32_e32 v81, v250, v129, vcc
	v_max3_f32 v98, v98, v75, v94
	v_max3_f32 v99, v99, v96, v97
	v_max3_f32 v98, v98, v95, v78
	v_max3_f32 v99, v99, v80, v81
	v_max3_f32 v98, v98, v79, v99
	v_mov_b32_e32 v99, v98
	s_nop 1
	v_permlane32_swap_b32_e32 v98, v99
	v_max_f32_e32 v99, v99, v99
	v_max_f32_e32 v98, v98, v98
	v_max_f32_e32 v98, v98, v99
	v_sub_f32_e32 v98, v98, v0
	v_cmp_lt_f32_e32 vcc, s87, v98
	s_cmp_lg_u64 vcc, 0
	s_cselect_b64 s[0:1], -1, 0
	s_cbranch_vccnz .LBB0_396

.LBB0_403:
	v_mov_b32_e32 v0, v223
	s_or_b32 s88, s0, s67
	s_lshl_b64 s[0:1], s[88:89], 1
	v_lshlrev_b32_e32 v2, 9, v0
	v_ashrrev_i32_e32 v0, 2, v0
	s_add_u32 s0, s52, s0
	v_and_b32_e32 v2, 0x3e00, v2
	v_and_b32_e32 v0, -8, v0
	s_addc_u32 s1, s53, s1
	v_add_u32_e32 v0, v2, v0
	v_lshl_add_u64 v[6:7], v[0:1], 1, s[0:1]
	global_load_dwordx4 v[144:147], v[6:7], off
	global_load_dwordx4 v[148:151], v[6:7], off offset:32
	global_load_dwordx4 v[152:155], v[6:7], off offset:64
	global_load_dwordx4 v[156:159], v[6:7], off offset:96
	v_add_u32_e32 v240, s49, v235
	s_mov_b64 s[0:1], -1
	s_and_b64 vcc, exec, s[16:17]
	s_waitcnt vmcnt(3)
	s_waitcnt vmcnt(2)
	s_waitcnt vmcnt(1)
	s_waitcnt vmcnt(0)
	s_cbranch_vccz .LBB0_405
	s_waitcnt vmcnt(0) lgkmcnt(0)
	s_barrier
	s_mov_b64 s[0:1], 0

.LBB0_407:
	ds_read_b128 v[6:9], v233
	ds_read_b128 v[10:13], v233 offset:512
	ds_read_b128 v[46:49], v233 offset:2048
	ds_read_b128 v[50:53], v233 offset:2560
	s_andn2_b64 vcc, exec, s[6:7]
	s_waitcnt lgkmcnt(3)
	v_mfma_f32_32x32x16_bf16 v[18:33], v[6:9], v[144:147], 0
	s_waitcnt lgkmcnt(2)
	v_mfma_f32_32x32x16_bf16 v[2:17], v[10:13], v[144:147], 0
	s_waitcnt lgkmcnt(1)
	v_mfma_f32_32x32x16_bf16 v[18:33], v[46:49], v[148:151], v[18:33]
	s_waitcnt lgkmcnt(0)
	v_mfma_f32_32x32x16_bf16 v[2:17], v[50:53], v[148:151], v[2:17]
	ds_read_b128 v[42:45], v233 offset:4096
	ds_read_b128 v[46:49], v233 offset:4608
	s_waitcnt lgkmcnt(1)
	v_mfma_f32_32x32x16_bf16 v[18:33], v[42:45], v[152:155], v[18:33]
	s_waitcnt lgkmcnt(0)
	v_mfma_f32_32x32x16_bf16 v[2:17], v[46:49], v[152:155], v[2:17]
	ds_read_b128 v[38:41], v233 offset:6144
	ds_read_b128 v[42:45], v233 offset:6656
	s_waitcnt lgkmcnt(1)
	v_mfma_f32_32x32x16_bf16 v[18:33], v[38:41], v[156:159], v[18:33]
	s_waitcnt lgkmcnt(0)
	v_mfma_f32_32x32x16_bf16 v[2:17], v[42:45], v[156:159], v[2:17]
	s_cbranch_vccnz .LBB0_409
	s_mov_b32 s0, 0
	s_nop 0
	v_mbcnt_lo_u32_b32 v0, -1, s0
	v_mbcnt_hi_u32_b32 v0, -1, v0
	v_and_or_b32 v34, v0, 31, s50
	v_ashrrev_i32_e32 v0, 5, v0
	s_nop 0
	v_lshlrev_b32_e32 v0, 2, v0
	v_add_u32_e32 v35, 32, v0
	v_cmp_le_i32_e32 vcc, v35, v34
	v_add_u32_e32 v35, 33, v0
	s_nop 0
	v_cndmask_b32_e32 v2, v250, v2, vcc
	v_cmp_lt_i32_e32 vcc, v0, v34
	s_nop 1
	v_cndmask_b32_e32 v19, v250, v19, vcc
	v_cmp_le_i32_e32 vcc, v0, v34
	s_nop 1
	v_cndmask_b32_e32 v18, v250, v18, vcc
	v_cmp_le_i32_e32 vcc, v35, v34
	v_or_b32_e32 v35, 2, v0
	s_nop 0
	v_cndmask_b32_e32 v3, v250, v3, vcc
	v_cmp_le_i32_e32 vcc, v35, v34
	v_add_u32_e32 v35, 34, v0
	s_nop 0
	v_cndmask_b32_e32 v20, v250, v20, vcc
	v_cmp_le_i32_e32 vcc, v35, v34
	v_or_b32_e32 v35, 3, v0
	s_nop 0
	v_cndmask_b32_e32 v4, v250, v4, vcc
	v_cmp_le_i32_e32 vcc, v35, v34
	v_add_u32_e32 v35, 35, v0
	s_nop 0
	v_cndmask_b32_e32 v21, v250, v21, vcc
	v_cmp_le_i32_e32 vcc, v35, v34
	v_add_u32_e32 v35, 8, v0
	s_nop 0
	v_cndmask_b32_e32 v5, v250, v5, vcc
	v_cmp_le_i32_e32 vcc, v35, v34
	v_add_u32_e32 v35, 40, v0
	s_nop 0
	v_cndmask_b32_e32 v22, v250, v22, vcc
	v_cmp_le_i32_e32 vcc, v35, v34
	v_add_u32_e32 v35, 9, v0
	s_nop 0
	v_cndmask_b32_e32 v6, v250, v6, vcc
	v_cmp_le_i32_e32 vcc, v35, v34
	v_add_u32_e32 v35, 41, v0
	s_nop 0
	v_cndmask_b32_e32 v23, v250, v23, vcc
	v_cmp_le_i32_e32 vcc, v35, v34
	v_add_u32_e32 v35, 10, v0
	s_nop 0
	v_cndmask_b32_e32 v7, v250, v7, vcc
	v_cmp_le_i32_e32 vcc, v35, v34
	v_add_u32_e32 v35, 42, v0
	s_nop 0
	v_cndmask_b32_e32 v24, v250, v24, vcc
	v_cmp_le_i32_e32 vcc, v35, v34
	v_add_u32_e32 v35, 11, v0
	s_nop 0
	v_cndmask_b32_e32 v8, v250, v8, vcc
	v_cmp_le_i32_e32 vcc, v35, v34
	v_add_u32_e32 v35, 43, v0
	s_nop 0
	v_cndmask_b32_e32 v25, v250, v25, vcc
	v_cmp_le_i32_e32 vcc, v35, v34
	v_add_u32_e32 v35, 16, v0
	s_nop 0
	v_cndmask_b32_e32 v9, v250, v9, vcc
	v_cmp_le_i32_e32 vcc, v35, v34
	v_add_u32_e32 v35, 48, v0
	s_nop 0
	v_cndmask_b32_e32 v26, v250, v26, vcc
	v_cmp_le_i32_e32 vcc, v35, v34
	v_add_u32_e32 v35, 17, v0
	s_nop 0
	v_cndmask_b32_e32 v10, v250, v10, vcc
	v_cmp_le_i32_e32 vcc, v35, v34
	v_add_u32_e32 v35, 49, v0
	s_nop 0
	v_cndmask_b32_e32 v27, v250, v27, vcc
	v_cmp_le_i32_e32 vcc, v35, v34
	v_add_u32_e32 v35, 18, v0
	s_nop 0
	v_cndmask_b32_e32 v11, v250, v11, vcc
	v_cmp_le_i32_e32 vcc, v35, v34
	v_add_u32_e32 v35, 50, v0
	s_nop 0
	v_cndmask_b32_e32 v28, v250, v28, vcc
	v_cmp_le_i32_e32 vcc, v35, v34
	v_add_u32_e32 v35, 19, v0
	s_nop 0
	v_cndmask_b32_e32 v12, v250, v12, vcc
	v_cmp_le_i32_e32 vcc, v35, v34
	v_add_u32_e32 v35, 51, v0
	s_nop 0
	v_cndmask_b32_e32 v29, v250, v29, vcc
	v_cmp_le_i32_e32 vcc, v35, v34
	v_add_u32_e32 v35, 24, v0
	s_nop 0
	v_cndmask_b32_e32 v13, v250, v13, vcc
	v_cmp_le_i32_e32 vcc, v35, v34
	v_add_u32_e32 v35, 56, v0
	s_nop 0
	v_cndmask_b32_e32 v30, v250, v30, vcc
	v_cmp_le_i32_e32 vcc, v35, v34
	v_add_u32_e32 v35, 25, v0
	s_nop 0
	v_cndmask_b32_e32 v14, v250, v14, vcc
	v_cmp_le_i32_e32 vcc, v35, v34
	v_add_u32_e32 v35, 57, v0
	s_nop 0
	v_cndmask_b32_e32 v31, v250, v31, vcc
	v_cmp_le_i32_e32 vcc, v35, v34
	v_add_u32_e32 v35, 26, v0
	s_nop 0
	v_cndmask_b32_e32 v15, v250, v15, vcc
	v_cmp_le_i32_e32 vcc, v35, v34
	v_add_u32_e32 v35, 58, v0
	s_nop 0
	v_cndmask_b32_e32 v32, v250, v32, vcc
	v_cmp_le_i32_e32 vcc, v35, v34
	v_add_u32_e32 v35, 27, v0
	v_add_u32_e32 v0, 59, v0
	v_cndmask_b32_e32 v16, v250, v16, vcc
	v_cmp_le_i32_e32 vcc, v35, v34
	s_nop 1
	v_cndmask_b32_e32 v33, v250, v33, vcc
	v_cmp_le_i32_e32 vcc, v0, v34
	s_nop 1
	v_cndmask_b32_e32 v17, v250, v17, vcc
.LBB0_409:
	s_nop 8
	v_max_f32_e32 v0, v19, v19
	v_max_f32_e32 v34, v18, v18
	v_max_f32_e32 v0, v34, v0
	v_max3_f32 v34, v20, v21, v3
	v_max3_f32 v0, v0, v2, v4
	v_max3_f32 v0, v0, v5, v22
	v_max3_f32 v34, v34, v24, v25
	v_max3_f32 v0, v0, v23, v6
	v_max3_f32 v34, v34, v8, v9
	v_max3_f32 v0, v0, v7, v26
	v_max3_f32 v34, v34, v28, v29
	v_max3_f32 v0, v0, v27, v10
	v_max3_f32 v34, v34, v12, v13
	v_max3_f32 v0, v0, v11, v30
	v_max3_f32 v34, v34, v32, v33
	v_max3_f32 v0, v0, v31, v14
	v_max3_f32 v34, v34, v16, v17
	v_max3_f32 v0, v0, v15, v34
	v_mov_b32_e32 v34, v0
	s_nop 1
	v_permlane32_swap_b32_e32 v0, v34
	v_max_f32_e32 v34, v34, v34
	v_max_f32_e32 v0, v0, v0
	v_max_f32_e32 v239, v0, v34
	v_sub_f32_e32 v0, v18, v239
	v_exp_f32_e32 v96, v0
	v_sub_f32_e32 v0, v2, v239
	v_exp_f32_e32 v80, v0
	v_sub_f32_e32 v0, v19, v239
	v_exp_f32_e32 v97, v0
	v_sub_f32_e32 v0, v3, v239
	v_exp_f32_e32 v81, v0
	v_sub_f32_e32 v0, v20, v239
	v_exp_f32_e32 v98, v0
	v_sub_f32_e32 v0, v4, v239
	v_exp_f32_e32 v82, v0
	v_sub_f32_e32 v0, v21, v239
	v_exp_f32_e32 v99, v0
	v_sub_f32_e32 v0, v5, v239
	v_exp_f32_e32 v83, v0
	v_sub_f32_e32 v0, v22, v239
	v_exp_f32_e32 v100, v0
	v_sub_f32_e32 v0, v6, v239
	v_exp_f32_e32 v84, v0
	v_sub_f32_e32 v0, v23, v239
	v_exp_f32_e32 v101, v0
	v_sub_f32_e32 v0, v7, v239
	v_exp_f32_e32 v85, v0
	v_sub_f32_e32 v0, v24, v239
	v_exp_f32_e32 v102, v0
	v_sub_f32_e32 v0, v8, v239
	v_exp_f32_e32 v86, v0
	v_sub_f32_e32 v0, v25, v239
	v_exp_f32_e32 v103, v0
	v_sub_f32_e32 v0, v9, v239
	v_exp_f32_e32 v87, v0
	v_sub_f32_e32 v0, v26, v239
	v_exp_f32_e32 v104, v0
	v_sub_f32_e32 v0, v10, v239
	v_exp_f32_e32 v88, v0
	v_sub_f32_e32 v0, v27, v239
	v_exp_f32_e32 v105, v0
	v_sub_f32_e32 v0, v11, v239
	v_exp_f32_e32 v89, v0
	v_sub_f32_e32 v0, v28, v239
	v_exp_f32_e32 v106, v0
	v_sub_f32_e32 v0, v12, v239
	s_cmp_lg_u32 0, -1
	v_exp_f32_e32 v90, v0
	v_sub_f32_e32 v0, v29, v239
	s_cselect_b32 s0, 0, 0
	v_exp_f32_e32 v107, v0
	v_sub_f32_e32 v0, v13, v239
	s_add_i32 s0, s0, s45
	v_exp_f32_e32 v91, v0
	v_sub_f32_e32 v0, v30, v239
	s_waitcnt vmcnt(0) lgkmcnt(0)
	s_barrier
	s_add_i32 s1, s0, 0x6000
	v_exp_f32_e32 v108, v0
	v_sub_f32_e32 v0, v14, v239
	s_mov_b32 s2, m0
	s_mov_b32 m0, s1
	s_nop 3
	global_load_lds_dwordx4 v236, s[24:25]
	s_mov_b32 m0, s2
	s_add_u32 s24, s24, 0x10000
	v_exp_f32_e32 v92, v0
	v_sub_f32_e32 v0, v31, v239
	s_addc_u32 s25, s25, 0
	s_add_i32 s1, s0, 0xc000
	s_mov_b32 s2, m0
	s_mov_b32 m0, s1
	s_nop 3
	global_load_lds_dwordx4 v237, s[14:15]
	s_mov_b32 m0, s2
	v_exp_f32_e32 v109, v0
	v_sub_f32_e32 v0, v15, v239
	s_add_i32 s0, s0, 0xe000
	s_mov_b32 s1, m0
	s_mov_b32 m0, s0
	s_nop 3
	global_load_lds_dwordx4 v238, s[14:15]
	s_mov_b32 m0, s1
	v_exp_f32_e32 v93, v0
	v_sub_f32_e32 v0, v32, v239
	ds_read_b128 v[204:207], v233 offset:8192
	ds_read_b128 v[196:199], v233 offset:8704
	ds_read_b128 v[200:203], v233 offset:10240
	ds_read_b128 v[192:195], v233 offset:10752
	v_exp_f32_e32 v110, v0
	v_sub_f32_e32 v0, v16, v239
	v_exp_f32_e32 v94, v0
	v_sub_f32_e32 v0, v33, v239
	v_exp_f32_e32 v111, v0
	v_sub_f32_e32 v0, v17, v239
	v_exp_f32_e32 v95, v0
	s_add_u32 s14, s14, 0x10000
	s_mov_b32 s4, 0
	s_addc_u32 s15, s15, 0
	s_andn2_b64 vcc, exec, s[8:9]
	s_mov_b32 s72, 1
	s_cbranch_vccnz .LBB0_425
	v_mov_b32_e32 v14, v1
	v_mov_b32_e32 v15, v1
	v_mov_b32_e32 v0, v1
	v_mov_b32_e32 v2, v1
	v_mov_b32_e32 v3, v1
	v_mov_b32_e32 v4, v1
	v_mov_b32_e32 v5, v1
	v_mov_b32_e32 v6, v1
	v_mov_b32_e32 v7, v1
	v_mov_b32_e32 v8, v1
	v_mov_b32_e32 v9, v1
	v_mov_b32_e32 v10, v1
	v_mov_b32_e32 v11, v1
	v_mov_b32_e32 v12, v1
	v_mov_b32_e32 v13, v1
	v_mov_b64_e32 v[78:79], v[14:15]
	v_mov_b64_e32 v[62:63], v[14:15]
	v_mov_b64_e32 v[46:47], v[14:15]
	v_mov_b64_e32 v[30:31], v[14:15]
	s_mov_b32 s0, 0
	s_mov_b32 s4, 0x8000
	s_movk_i32 s70, 0x4000
	s_movk_i32 s74, 0x2000
	v_mov_b32_e32 v241, 0
	s_mov_b32 s5, 6
	v_mov_b64_e32 v[76:77], v[12:13]
	v_mov_b64_e32 v[74:75], v[10:11]
	v_mov_b64_e32 v[72:73], v[8:9]
	v_mov_b64_e32 v[70:71], v[6:7]
	v_mov_b64_e32 v[68:69], v[4:5]
	v_mov_b64_e32 v[66:67], v[2:3]
	v_mov_b64_e32 v[64:65], v[0:1]
	v_mov_b64_e32 v[60:61], v[12:13]
	v_mov_b64_e32 v[58:59], v[10:11]
	v_mov_b64_e32 v[56:57], v[8:9]
	v_mov_b64_e32 v[54:55], v[6:7]
	v_mov_b64_e32 v[52:53], v[4:5]
	v_mov_b64_e32 v[50:51], v[2:3]
	v_mov_b64_e32 v[48:49], v[0:1]
	v_mov_b64_e32 v[44:45], v[12:13]
	v_mov_b64_e32 v[42:43], v[10:11]
	v_mov_b64_e32 v[40:41], v[8:9]
	v_mov_b64_e32 v[38:39], v[6:7]
	v_mov_b64_e32 v[36:37], v[4:5]
	v_mov_b64_e32 v[34:35], v[2:3]
	v_mov_b64_e32 v[32:33], v[0:1]
	v_mov_b64_e32 v[28:29], v[12:13]
	v_mov_b64_e32 v[26:27], v[10:11]
	v_mov_b64_e32 v[24:25], v[8:9]
	v_mov_b64_e32 v[22:23], v[6:7]
	v_mov_b64_e32 v[20:21], v[4:5]
	v_mov_b64_e32 v[18:19], v[2:3]
	v_mov_b64_e32 v[16:17], v[0:1]
	s_movk_i32 s40, 0x4000
	s_waitcnt lgkmcnt(0)
.LBB0_411:
	v_add_u32_e32 v14, s0, v234
	v_add_u32_e32 v0, s74, v233
	ds_read_b64_tr_b16 v[214:215], v14 offset:33280
	ds_read_b128 v[216:219], v0 offset:4096
	ds_read_b64_tr_b16 v[212:213], v14 offset:32768
	s_waitcnt lgkmcnt(6)
	v_mfma_f32_32x32x16_bf16 v[128:143], v[204:207], v[144:147], 0
	v_add_f32_e32 v2, v96, v97
	v_add_f32_e32 v2, v98, v2
	v_add_f32_e32 v2, v99, v2
	v_add_f32_e32 v2, v100, v2
	v_add_f32_e32 v2, v101, v2
	v_cvt_pk_bf16_f32 v188, v96, v97
	v_cvt_pk_bf16_f32 v189, v98, v99
	ds_read_b64_tr_b16 v[204:205], v14 offset:36864
	ds_read_b64_tr_b16 v[206:207], v14 offset:37376
	ds_read_b128 v[226:229], v0 offset:4608
	s_waitcnt lgkmcnt(8)
	v_mfma_f32_32x32x16_bf16 v[112:127], v[196:199], v[144:147], 0
	v_add_f32_e32 v2, v102, v2
	v_add_f32_e32 v2, v103, v2
	v_add_f32_e32 v2, v104, v2
	v_add_f32_e32 v6, v105, v2
	v_cvt_pk_bf16_f32 v190, v100, v101
	v_cvt_pk_bf16_f32 v191, v102, v103
	ds_read_b64_tr_b16 v[4:5], v14 offset:34304
	ds_read_b128 v[100:103], v0 offset:6144
	ds_read_b64_tr_b16 v[2:3], v14 offset:33792
	s_waitcnt lgkmcnt(10)
	v_mfma_f32_32x32x16_bf16 v[128:143], v[200:203], v[148:151], v[128:143]
	v_add_f32_e32 v6, v106, v6
	v_add_f32_e32 v6, v107, v6
	v_add_f32_e32 v6, v108, v6
	v_add_f32_e32 v15, v109, v6
	v_cvt_pk_bf16_f32 v184, v104, v105
	v_cvt_pk_bf16_f32 v185, v106, v107
	ds_read_b64_tr_b16 v[6:7], v14 offset:37888
	ds_read_b64_tr_b16 v[8:9], v14 offset:38400
	ds_read_b128 v[104:107], v0 offset:6656
	s_waitcnt lgkmcnt(12)
	v_mfma_f32_32x32x16_bf16 v[112:127], v[192:195], v[148:151], v[112:127]
	v_add_f32_e32 v0, v110, v15
	v_add_f32_e32 v0, v111, v0
	v_add_f32_e32 v0, v80, v0
	v_add_f32_e32 v0, v81, v0
	v_cvt_pk_bf16_f32 v186, v108, v109
	v_cvt_pk_bf16_f32 v187, v110, v111
	ds_read_b64_tr_b16 v[12:13], v14 offset:35328
	ds_read_b64_tr_b16 v[10:11], v14 offset:34816
	s_waitcnt lgkmcnt(12)
	v_mfma_f32_32x32x16_bf16 v[128:143], v[216:219], v[152:155], v[128:143]
	v_add_f32_e32 v0, v82, v0
	v_add_f32_e32 v0, v83, v0
	v_add_f32_e32 v0, v84, v0
	v_add_f32_e32 v0, v85, v0
	v_cvt_pk_bf16_f32 v180, v80, v81
	v_cvt_pk_bf16_f32 v181, v82, v83
	ds_read_b64_tr_b16 v[96:97], v14 offset:38912
	ds_read_b64_tr_b16 v[98:99], v14 offset:39424
	s_waitcnt lgkmcnt(10)
	v_mfma_f32_32x32x16_bf16 v[112:127], v[226:229], v[152:155], v[112:127]
	v_add_f32_e32 v0, v86, v0
	v_add_f32_e32 v0, v87, v0
	v_add_f32_e32 v0, v88, v0
	v_add_f32_e32 v0, v89, v0
	v_cvt_pk_bf16_f32 v182, v84, v85
	v_cvt_pk_bf16_f32 v183, v86, v87
	ds_read_b64_tr_b16 v[84:85], v14 offset:35840
	ds_read_b64_tr_b16 v[86:87], v14 offset:36352
	s_waitcnt lgkmcnt(10)
	v_mfma_f32_32x32x16_bf16 v[128:143], v[100:103], v[156:159], v[128:143]
	v_add_f32_e32 v0, v90, v0
	v_add_f32_e32 v0, v91, v0
	v_add_f32_e32 v0, v92, v0
	v_add_f32_e32 v0, v93, v0
	v_cvt_pk_bf16_f32 v176, v88, v89
	v_cvt_pk_bf16_f32 v177, v90, v91
	ds_read_b64_tr_b16 v[80:81], v14 offset:39936
	ds_read_b64_tr_b16 v[82:83], v14 offset:40448
	s_waitcnt lgkmcnt(8)
	v_mfma_f32_32x32x16_bf16 v[112:127], v[104:107], v[156:159], v[112:127]
	v_add_f32_e32 v0, v94, v0
	v_add_f32_e32 v0, v95, v0
	v_add_f32_e32 v0, 0, v0
	v_cvt_pk_bf16_f32 v178, v92, v93
	v_cvt_pk_bf16_f32 v179, v94, v95
	v_max_f32_e32 v15, v129, v129
	v_max_f32_e32 v88, v128, v128
	v_max_f32_e32 v15, v88, v15
	s_nop 3
	v_max3_f32 v88, v130, v131, v113
	v_max3_f32 v15, v15, v112, v114
	v_max3_f32 v15, v15, v115, v132
	v_max3_f32 v88, v88, v134, v135
	v_max3_f32 v15, v15, v133, v116
	v_max3_f32 v88, v88, v118, v119
	v_max3_f32 v15, v15, v117, v136
	v_max3_f32 v88, v88, v138, v139
	v_max3_f32 v15, v15, v137, v120
	v_max3_f32 v88, v88, v122, v123
	v_max3_f32 v15, v15, v121, v140
	v_max3_f32 v88, v88, v142, v143
	v_max3_f32 v15, v15, v141, v124
	v_max3_f32 v88, v88, v126, v127
	v_max3_f32 v15, v15, v125, v88
	s_add_i32 s0, s74, 0xffffe000
	v_mov_b32_e32 v88, v15
	s_cmp_lg_u32 s74, 0
	s_nop 0
	v_permlane32_swap_b32_e32 v15, v88
	s_cselect_b32 s0, s0, 0x6000
	v_max_f32_e32 v88, v88, v88
	v_max_f32_e32 v15, v15, v15
	s_add_i32 s0, s0, s46
	s_mov_b32 s1, m0
	s_mov_b32 m0, s0
	s_nop 3
	global_load_lds_dwordx4 v236, s[24:25]
	s_mov_b32 m0, s1
	v_max_f32_e32 v15, v15, v88
	s_add_i32 s0, s4, s47
	s_mov_b32 s1, m0
	s_mov_b32 m0, s0
	s_nop 3
	global_load_lds_dwordx4 v237, s[14:15]
	s_mov_b32 m0, s1
	v_sub_f32_e32 v15, v15, v239
	s_addk_i32 s0, 0x2000
	s_mov_b32 s1, m0
	s_mov_b32 m0, s0
	s_nop 3
	global_load_lds_dwordx4 v238, s[14:15]
	s_mov_b32 m0, s1
	v_cmp_lt_f32_e32 vcc, s87, v15
	s_cmp_lg_u64 vcc, 0
	v_add_f32_e32 v0, v241, v0
	s_cselect_b64 s[0:1], -1, 0
	s_cbranch_vccnz .LBB0_419
.LBB0_412:
	v_mfma_f32_32x32x16_bf16 v[64:79], v[188:191], v[212:215], v[64:79]
	v_sub_f32_e32 v15, v128, v239
	v_exp_f32_e32 v128, v15
	v_sub_f32_e32 v15, v129, v239
	v_exp_f32_e32 v129, v15
	ds_read_b64_tr_b16 v[88:89], v14 offset:40960
	ds_read_b64_tr_b16 v[90:91], v14 offset:41472
	v_mfma_f32_32x32x16_bf16 v[48:63], v[188:191], v[204:207], v[48:63]
	v_sub_f32_e32 v15, v130, v239
	v_exp_f32_e32 v130, v15
	v_sub_f32_e32 v15, v131, v239
	v_exp_f32_e32 v131, v15
	ds_read_b64_tr_b16 v[92:93], v14 offset:45056
	ds_read_b64_tr_b16 v[94:95], v14 offset:45568
	v_mfma_f32_32x32x16_bf16 v[64:79], v[184:187], v[2:5], v[64:79]
	v_sub_f32_e32 v2, v132, v239
	v_exp_f32_e32 v132, v2
	v_sub_f32_e32 v2, v133, v239
	v_exp_f32_e32 v133, v2
	ds_read_b64_tr_b16 v[2:3], v14 offset:41984
	ds_read_b64_tr_b16 v[4:5], v14 offset:42496
	v_mfma_f32_32x32x16_bf16 v[48:63], v[184:187], v[6:9], v[48:63]
	v_sub_f32_e32 v6, v134, v239
	v_exp_f32_e32 v134, v6
	v_sub_f32_e32 v6, v135, v239
	v_exp_f32_e32 v135, v6
	ds_read_b64_tr_b16 v[6:7], v14 offset:46080
	ds_read_b64_tr_b16 v[8:9], v14 offset:46592
	s_waitcnt lgkmcnt(14)
	v_mfma_f32_32x32x16_bf16 v[64:79], v[180:183], v[10:13], v[64:79]
	v_sub_f32_e32 v10, v136, v239
	v_exp_f32_e32 v136, v10
	v_sub_f32_e32 v10, v137, v239
	v_exp_f32_e32 v137, v10
	ds_read_b64_tr_b16 v[10:11], v14 offset:43008
	ds_read_b64_tr_b16 v[12:13], v14 offset:43520
	s_waitcnt lgkmcnt(14)
	v_mfma_f32_32x32x16_bf16 v[48:63], v[180:183], v[96:99], v[48:63]
	v_sub_f32_e32 v15, v138, v239
	v_exp_f32_e32 v138, v15
	v_sub_f32_e32 v15, v139, v239
	v_exp_f32_e32 v139, v15
	ds_read_b64_tr_b16 v[96:97], v14 offset:47104
	ds_read_b64_tr_b16 v[98:99], v14 offset:47616
	s_waitcnt lgkmcnt(14)
	v_mfma_f32_32x32x16_bf16 v[64:79], v[176:179], v[84:87], v[64:79]
	v_sub_f32_e32 v15, v140, v239
	v_exp_f32_e32 v140, v15
	v_sub_f32_e32 v15, v141, v239
	v_exp_f32_e32 v141, v15
	ds_read_b64_tr_b16 v[84:85], v14 offset:44032
	ds_read_b64_tr_b16 v[86:87], v14 offset:44544
	s_waitcnt lgkmcnt(14)
	v_mfma_f32_32x32x16_bf16 v[48:63], v[176:179], v[80:83], v[48:63]
	v_sub_f32_e32 v15, v142, v239
	v_exp_f32_e32 v142, v15
	v_sub_f32_e32 v15, v143, v239
	v_exp_f32_e32 v143, v15
	ds_read_b64_tr_b16 v[100:101], v14 offset:48128
	ds_read_b64_tr_b16 v[102:103], v14 offset:48640
	s_waitcnt lgkmcnt(14)
	v_mfma_f32_32x32x16_bf16 v[32:47], v[188:191], v[88:91], v[32:47]
	v_sub_f32_e32 v14, v112, v239
	v_exp_f32_e32 v112, v14
	v_sub_f32_e32 v14, v113, v239
	v_exp_f32_e32 v113, v14
	s_waitcnt lgkmcnt(12)
	v_mfma_f32_32x32x16_bf16 v[16:31], v[188:191], v[92:95], v[16:31]
	v_sub_f32_e32 v14, v114, v239
	v_exp_f32_e32 v114, v14
	v_sub_f32_e32 v14, v115, v239
	v_exp_f32_e32 v115, v14
	s_waitcnt lgkmcnt(10)
	v_mfma_f32_32x32x16_bf16 v[32:47], v[184:187], v[2:5], v[32:47]
	v_sub_f32_e32 v2, v116, v239
	v_exp_f32_e32 v116, v2
	v_sub_f32_e32 v2, v117, v239
	v_exp_f32_e32 v117, v2
	s_waitcnt lgkmcnt(8)
	v_mfma_f32_32x32x16_bf16 v[16:31], v[184:187], v[6:9], v[16:31]
	v_sub_f32_e32 v2, v118, v239
	v_exp_f32_e32 v118, v2
	v_sub_f32_e32 v2, v119, v239
	v_exp_f32_e32 v119, v2
	v_add_u32_e32 v15, s70, v233
	ds_read_b128 v[2:5], v15
	s_waitcnt lgkmcnt(7)
	v_mfma_f32_32x32x16_bf16 v[32:47], v[180:183], v[10:13], v[32:47]
	v_sub_f32_e32 v6, v120, v239
	v_exp_f32_e32 v120, v6
	v_sub_f32_e32 v6, v121, v239
	v_exp_f32_e32 v121, v6
	ds_read_b128 v[6:9], v15 offset:512
	s_waitcnt lgkmcnt(6)
	v_mfma_f32_32x32x16_bf16 v[16:31], v[180:183], v[96:99], v[16:31]
	v_sub_f32_e32 v10, v122, v239
	v_exp_f32_e32 v122, v10
	v_sub_f32_e32 v10, v123, v239
	v_exp_f32_e32 v123, v10
	ds_read_b128 v[192:195], v15 offset:2048
	s_waitcnt lgkmcnt(5)
	v_mfma_f32_32x32x16_bf16 v[32:47], v[176:179], v[84:87], v[32:47]
	v_sub_f32_e32 v10, v124, v239
	v_exp_f32_e32 v124, v10
	v_sub_f32_e32 v10, v125, v239
	v_exp_f32_e32 v125, v10
	ds_read_b128 v[10:13], v15 offset:2560
	s_waitcnt lgkmcnt(4)
	v_mfma_f32_32x32x16_bf16 v[16:31], v[176:179], v[100:103], v[16:31]
	v_sub_f32_e32 v14, v126, v239
	v_exp_f32_e32 v126, v14
	v_sub_f32_e32 v14, v127, v239
	v_exp_f32_e32 v127, v14
	s_waitcnt vmcnt(3) lgkmcnt(4)
	s_barrier
	s_andn2_b64 vcc, exec, s[0:1]
	s_cbranch_vccnz .LBB0_414
	s_waitcnt lgkmcnt(0)
	s_mov_b32 s0, 0
	s_nop 0
	v_mbcnt_lo_u32_b32 v14, -1, s0
	v_mbcnt_hi_u32_b32 v14, -1, v14
	v_ashrrev_i32_e32 v14, 3, v14
	v_lshlrev_b32_e32 v14, 2, v14
	v_and_b32_e32 v14, -16, v14
	v_add_u32_e32 v14, s51, v14
	ds_read_b128 v[84:87], v14 offset:96
	ds_read_b128 v[88:91], v14 offset:64
	ds_read_b128 v[92:95], v14 offset:32
	ds_read_b128 v[96:99], v14
	s_waitcnt lgkmcnt(3)
	v_pk_mul_f32 v[76:77], v[76:77], v[84:85]
	s_waitcnt lgkmcnt(2)
	v_pk_mul_f32 v[72:73], v[72:73], v[88:89]
	s_waitcnt lgkmcnt(1)
	v_pk_mul_f32 v[68:69], v[68:69], v[92:93]
	v_pk_mul_f32 v[78:79], v[78:79], v[86:87]
	v_pk_mul_f32 v[74:75], v[74:75], v[90:91]
	v_pk_mul_f32 v[70:71], v[70:71], v[94:95]
	s_waitcnt lgkmcnt(0)
	v_pk_mul_f32 v[66:67], v[66:67], v[98:99]
	v_pk_mul_f32 v[64:65], v[64:65], v[96:97]
	v_pk_mul_f32 v[60:61], v[60:61], v[84:85]
	v_pk_mul_f32 v[56:57], v[56:57], v[88:89]
	v_pk_mul_f32 v[52:53], v[52:53], v[92:93]
	v_pk_mul_f32 v[62:63], v[62:63], v[86:87]
	v_pk_mul_f32 v[58:59], v[58:59], v[90:91]
	v_pk_mul_f32 v[54:55], v[54:55], v[94:95]
	v_pk_mul_f32 v[50:51], v[50:51], v[98:99]
	v_pk_mul_f32 v[48:49], v[48:49], v[96:97]
	v_pk_mul_f32 v[44:45], v[44:45], v[84:85]
	v_pk_mul_f32 v[40:41], v[40:41], v[88:89]
	v_pk_mul_f32 v[36:37], v[36:37], v[92:93]
	v_pk_mul_f32 v[46:47], v[46:47], v[86:87]
	v_pk_mul_f32 v[42:43], v[42:43], v[90:91]
	v_pk_mul_f32 v[38:39], v[38:39], v[94:95]
	v_pk_mul_f32 v[34:35], v[34:35], v[98:99]
	v_pk_mul_f32 v[32:33], v[32:33], v[96:97]
	v_pk_mul_f32 v[28:29], v[28:29], v[84:85]
	v_pk_mul_f32 v[24:25], v[24:25], v[88:89]
	v_pk_mul_f32 v[20:21], v[20:21], v[92:93]
	v_pk_mul_f32 v[30:31], v[30:31], v[86:87]
	v_pk_mul_f32 v[26:27], v[26:27], v[90:91]
	v_pk_mul_f32 v[22:23], v[22:23], v[94:95]
	v_pk_mul_f32 v[18:19], v[18:19], v[98:99]
	v_pk_mul_f32 v[16:17], v[16:17], v[96:97]
.LBB0_414:
	s_add_u32 s2, s24, 0x10000
	s_addc_u32 s3, s25, 0
	s_add_u32 s0, s14, 0x10000
	s_addc_u32 s1, s15, 0
	s_add_i32 s41, s4, 0x4000
	s_cmpk_lg_u32 s4, 0x8000
	s_cselect_b32 s69, s41, 0
	v_add_u32_e32 v14, s40, v234
	ds_read_b64_tr_b16 v[200:201], v14 offset:32768
	ds_read_b64_tr_b16 v[202:203], v14 offset:33280
	ds_read_b128 v[204:207], v15 offset:4096
	s_waitcnt lgkmcnt(6)
	v_mfma_f32_32x32x16_bf16 v[96:111], v[2:5], v[144:147], 0
	v_add_f32_e32 v84, v128, v129
	v_add_f32_e32 v84, v130, v84
	v_add_f32_e32 v84, v131, v84
	v_add_f32_e32 v84, v132, v84
	v_add_f32_e32 v84, v133, v84
	v_cvt_pk_bf16_f32 v188, v128, v129
	v_cvt_pk_bf16_f32 v189, v130, v131
	ds_read_b64_tr_b16 v[198:199], v14 offset:37376
	ds_read_b64_tr_b16 v[196:197], v14 offset:36864
	ds_read_b128 v[212:215], v15 offset:4608
	v_add_f32_e32 v2, v134, v84
	s_waitcnt lgkmcnt(8)
	v_mfma_f32_32x32x16_bf16 v[80:95], v[6:9], v[144:147], 0
	v_add_f32_e32 v2, v135, v2
	v_add_f32_e32 v2, v136, v2
	v_add_f32_e32 v128, v137, v2
	v_cvt_pk_bf16_f32 v190, v132, v133
	v_cvt_pk_bf16_f32 v191, v134, v135
	ds_read_b64_tr_b16 v[2:3], v14 offset:33792
	ds_read_b64_tr_b16 v[4:5], v14 offset:34304
	ds_read_b128 v[132:135], v15 offset:6144
	s_waitcnt lgkmcnt(10)
	v_mfma_f32_32x32x16_bf16 v[96:111], v[192:195], v[148:151], v[96:111]
	v_add_f32_e32 v6, v138, v128
	v_add_f32_e32 v6, v139, v6
	v_add_f32_e32 v6, v140, v6
	v_add_f32_e32 v128, v141, v6
	v_cvt_pk_bf16_f32 v184, v136, v137
	v_cvt_pk_bf16_f32 v185, v138, v139
	ds_read_b64_tr_b16 v[8:9], v14 offset:38400
	ds_read_b64_tr_b16 v[6:7], v14 offset:37888
	ds_read_b128 v[136:139], v15 offset:6656
	s_waitcnt lgkmcnt(12)
	v_mfma_f32_32x32x16_bf16 v[80:95], v[10:13], v[148:151], v[80:95]
	v_add_f32_e32 v10, v142, v128
	v_add_f32_e32 v10, v143, v10
	v_add_f32_e32 v10, v112, v10
	v_add_f32_e32 v15, v113, v10
	v_cvt_pk_bf16_f32 v186, v140, v141
	v_cvt_pk_bf16_f32 v187, v142, v143
	ds_read_b64_tr_b16 v[12:13], v14 offset:35328
	ds_read_b64_tr_b16 v[10:11], v14 offset:34816
	s_waitcnt lgkmcnt(11)
	v_mfma_f32_32x32x16_bf16 v[96:111], v[204:207], v[152:155], v[96:111]
	v_add_f32_e32 v15, v114, v15
	v_add_f32_e32 v15, v115, v15
	v_add_f32_e32 v15, v116, v15
	v_add_f32_e32 v15, v117, v15
	v_cvt_pk_bf16_f32 v180, v112, v113
	v_cvt_pk_bf16_f32 v181, v114, v115
	ds_read_b64_tr_b16 v[128:129], v14 offset:38912
	ds_read_b64_tr_b16 v[130:131], v14 offset:39424
	s_waitcnt lgkmcnt(10)
	v_mfma_f32_32x32x16_bf16 v[80:95], v[212:215], v[152:155], v[80:95]
	v_add_f32_e32 v15, v118, v15
	v_add_f32_e32 v15, v119, v15
	v_add_f32_e32 v15, v120, v15
	v_add_f32_e32 v15, v121, v15
	v_cvt_pk_bf16_f32 v182, v116, v117
	v_cvt_pk_bf16_f32 v183, v118, v119
	ds_read_b64_tr_b16 v[116:117], v14 offset:35840
	ds_read_b64_tr_b16 v[118:119], v14 offset:36352
	s_waitcnt lgkmcnt(9)
	v_mfma_f32_32x32x16_bf16 v[96:111], v[132:135], v[156:159], v[96:111]
	v_add_f32_e32 v15, v122, v15
	v_add_f32_e32 v15, v123, v15
	v_add_f32_e32 v15, v124, v15
	v_add_f32_e32 v15, v125, v15
	v_cvt_pk_bf16_f32 v176, v120, v121
	v_cvt_pk_bf16_f32 v177, v122, v123
	ds_read_b64_tr_b16 v[112:113], v14 offset:39936
	ds_read_b64_tr_b16 v[114:115], v14 offset:40448
	s_waitcnt lgkmcnt(8)
	v_mfma_f32_32x32x16_bf16 v[80:95], v[136:139], v[156:159], v[80:95]
	v_add_f32_e32 v15, v126, v15
	v_add_f32_e32 v15, v127, v15
	v_add_f32_e32 v15, 0, v15
	v_cvt_pk_bf16_f32 v178, v124, v125
	v_cvt_pk_bf16_f32 v179, v126, v127
	s_nop 0
	v_add_f32_e32 v241, v0, v15
	v_max_f32_e32 v0, v97, v97
	v_max_f32_e32 v15, v96, v96
	v_max_f32_e32 v0, v15, v0
	s_nop 1
	v_max3_f32 v15, v98, v99, v81
	v_max3_f32 v0, v0, v80, v82
	v_max3_f32 v0, v0, v83, v100
	v_max3_f32 v15, v15, v102, v103
	v_max3_f32 v0, v0, v101, v84
	v_max3_f32 v15, v15, v86, v87
	v_max3_f32 v0, v0, v85, v104
	v_max3_f32 v15, v15, v106, v107
	v_max3_f32 v0, v0, v105, v88
	v_max3_f32 v15, v15, v90, v91
	v_max3_f32 v0, v0, v89, v108
	v_max3_f32 v15, v15, v110, v111
	v_max3_f32 v0, v0, v109, v92
	v_max3_f32 v15, v15, v94, v95
	v_max3_f32 v0, v0, v93, v15
	s_add_i32 s40, s70, 0xffffe000
	v_mov_b32_e32 v15, v0
	s_cmp_lg_u32 s70, 0
	s_nop 0
	v_permlane32_swap_b32_e32 v0, v15
	s_cselect_b32 s40, s40, 0x6000
	v_max_f32_e32 v15, v15, v15
	v_max_f32_e32 v0, v0, v0
	s_add_i32 s40, s40, s46
	s_mov_b32 s41, m0
	s_mov_b32 m0, s40
	s_nop 3
	global_load_lds_dwordx4 v236, s[2:3]
	s_mov_b32 m0, s41
	v_max_f32_e32 v0, v0, v15
	s_add_i32 s2, s69, s47
	s_mov_b32 s3, m0
	s_mov_b32 m0, s2
	s_nop 3
	global_load_lds_dwordx4 v237, s[0:1]
	s_mov_b32 m0, s3
	v_sub_f32_e32 v0, v0, v239
	s_addk_i32 s2, 0x2000
	s_mov_b32 s3, m0
	s_mov_b32 m0, s2
	s_nop 3
	global_load_lds_dwordx4 v238, s[0:1]
	s_mov_b32 m0, s3
	v_cmp_lt_f32_e32 vcc, s87, v0
	s_cmp_lg_u64 vcc, 0
	s_cselect_b64 s[0:1], -1, 0
	s_cbranch_vccnz .LBB0_422
.LBB0_415:
	s_add_i32 s2, s70, 0x2000
	s_cmpk_lg_i32 s70, 0x6000
	s_cselect_b32 s74, s2, 0
	v_mfma_f32_32x32x16_bf16 v[64:79], v[188:191], v[200:203], v[64:79]
	v_sub_f32_e32 v0, v96, v239
	v_exp_f32_e32 v96, v0
	v_sub_f32_e32 v0, v97, v239
	v_exp_f32_e32 v97, v0
	ds_read_b64_tr_b16 v[120:121], v14 offset:40960
	ds_read_b64_tr_b16 v[122:123], v14 offset:41472
	v_mfma_f32_32x32x16_bf16 v[48:63], v[188:191], v[196:199], v[48:63]
	v_sub_f32_e32 v0, v98, v239
	v_exp_f32_e32 v98, v0
	v_sub_f32_e32 v0, v99, v239
	v_exp_f32_e32 v99, v0
	ds_read_b64_tr_b16 v[124:125], v14 offset:45056
	ds_read_b64_tr_b16 v[126:127], v14 offset:45568
	v_mfma_f32_32x32x16_bf16 v[64:79], v[184:187], v[2:5], v[64:79]
	v_sub_f32_e32 v0, v100, v239
	v_exp_f32_e32 v100, v0
	v_sub_f32_e32 v0, v101, v239
	v_exp_f32_e32 v101, v0
	ds_read_b64_tr_b16 v[2:3], v14 offset:41984
	ds_read_b64_tr_b16 v[4:5], v14 offset:42496
	v_mfma_f32_32x32x16_bf16 v[48:63], v[184:187], v[6:9], v[48:63]
	v_sub_f32_e32 v0, v102, v239
	v_exp_f32_e32 v102, v0
	v_sub_f32_e32 v0, v103, v239
	v_exp_f32_e32 v103, v0
	ds_read_b64_tr_b16 v[6:7], v14 offset:46080
	ds_read_b64_tr_b16 v[8:9], v14 offset:46592
	s_waitcnt lgkmcnt(14)
	v_mfma_f32_32x32x16_bf16 v[64:79], v[180:183], v[10:13], v[64:79]
	v_sub_f32_e32 v0, v104, v239
	v_exp_f32_e32 v104, v0
	v_sub_f32_e32 v0, v105, v239
	v_exp_f32_e32 v105, v0
	ds_read_b64_tr_b16 v[10:11], v14 offset:43008
	ds_read_b64_tr_b16 v[12:13], v14 offset:43520
	s_waitcnt lgkmcnt(14)
	v_mfma_f32_32x32x16_bf16 v[48:63], v[180:183], v[128:131], v[48:63]
	v_sub_f32_e32 v0, v106, v239
	v_exp_f32_e32 v106, v0
	v_sub_f32_e32 v0, v107, v239
	v_exp_f32_e32 v107, v0
	ds_read_b64_tr_b16 v[128:129], v14 offset:47104
	ds_read_b64_tr_b16 v[130:131], v14 offset:47616
	s_waitcnt lgkmcnt(14)
	v_mfma_f32_32x32x16_bf16 v[64:79], v[176:179], v[116:119], v[64:79]
	v_sub_f32_e32 v0, v108, v239
	v_exp_f32_e32 v108, v0
	v_sub_f32_e32 v0, v109, v239
	v_exp_f32_e32 v109, v0
	ds_read_b64_tr_b16 v[116:117], v14 offset:44032
	ds_read_b64_tr_b16 v[118:119], v14 offset:44544
	s_waitcnt lgkmcnt(14)
	v_mfma_f32_32x32x16_bf16 v[48:63], v[176:179], v[112:115], v[48:63]
	v_sub_f32_e32 v0, v110, v239
	v_exp_f32_e32 v110, v0
	v_sub_f32_e32 v0, v111, v239
	v_exp_f32_e32 v111, v0
	ds_read_b64_tr_b16 v[112:113], v14 offset:48128
	ds_read_b64_tr_b16 v[114:115], v14 offset:48640
	s_waitcnt lgkmcnt(14)
	v_mfma_f32_32x32x16_bf16 v[32:47], v[188:191], v[120:123], v[32:47]
	v_sub_f32_e32 v0, v80, v239
	v_exp_f32_e32 v80, v0
	v_sub_f32_e32 v0, v81, v239
	v_exp_f32_e32 v81, v0
	s_waitcnt lgkmcnt(12)
	v_mfma_f32_32x32x16_bf16 v[16:31], v[188:191], v[124:127], v[16:31]
	v_sub_f32_e32 v0, v82, v239
	v_exp_f32_e32 v82, v0
	v_sub_f32_e32 v0, v83, v239
	v_exp_f32_e32 v83, v0
	s_waitcnt lgkmcnt(10)
	v_mfma_f32_32x32x16_bf16 v[32:47], v[184:187], v[2:5], v[32:47]
	v_sub_f32_e32 v0, v84, v239
	v_exp_f32_e32 v84, v0
	v_sub_f32_e32 v0, v85, v239
	v_exp_f32_e32 v85, v0
	s_waitcnt lgkmcnt(8)
	v_mfma_f32_32x32x16_bf16 v[16:31], v[184:187], v[6:9], v[16:31]
	v_sub_f32_e32 v0, v86, v239
	v_exp_f32_e32 v86, v0
	v_sub_f32_e32 v0, v87, v239
	v_exp_f32_e32 v87, v0
	v_add_u32_e32 v0, s74, v233
	ds_read_b128 v[204:207], v0
	s_waitcnt lgkmcnt(7)
	v_mfma_f32_32x32x16_bf16 v[32:47], v[180:183], v[10:13], v[32:47]
	v_sub_f32_e32 v2, v88, v239
	v_exp_f32_e32 v88, v2
	v_sub_f32_e32 v2, v89, v239
	v_exp_f32_e32 v89, v2
	ds_read_b128 v[196:199], v0 offset:512
	s_waitcnt lgkmcnt(6)
	v_mfma_f32_32x32x16_bf16 v[16:31], v[180:183], v[128:131], v[16:31]
	v_sub_f32_e32 v2, v90, v239
	v_exp_f32_e32 v90, v2
	v_sub_f32_e32 v2, v91, v239
	v_exp_f32_e32 v91, v2
	ds_read_b128 v[200:203], v0 offset:2048
	s_waitcnt lgkmcnt(5)
	v_mfma_f32_32x32x16_bf16 v[32:47], v[176:179], v[116:119], v[32:47]
	v_sub_f32_e32 v2, v92, v239
	v_exp_f32_e32 v92, v2
	v_sub_f32_e32 v2, v93, v239
	v_exp_f32_e32 v93, v2
	ds_read_b128 v[192:195], v0 offset:2560
	s_waitcnt lgkmcnt(4)
	v_mfma_f32_32x32x16_bf16 v[16:31], v[176:179], v[112:115], v[16:31]
	v_sub_f32_e32 v0, v94, v239
	v_exp_f32_e32 v94, v0
	v_sub_f32_e32 v0, v95, v239
	v_exp_f32_e32 v95, v0
	s_waitcnt vmcnt(3) lgkmcnt(4)
	s_barrier
	s_andn2_b64 vcc, exec, s[0:1]
	s_cbranch_vccnz .LBB0_417
	s_waitcnt lgkmcnt(0)
	s_mov_b32 s0, 0
	s_nop 0
	v_mbcnt_lo_u32_b32 v0, -1, s0
	v_mbcnt_hi_u32_b32 v0, -1, v0
	v_ashrrev_i32_e32 v0, 3, v0
	v_lshlrev_b32_e32 v0, 2, v0
	v_and_b32_e32 v0, -16, v0
	v_add_u32_e32 v0, s51, v0
	ds_read_b128 v[2:5], v0 offset:96
	ds_read_b128 v[6:9], v0 offset:64
	ds_read_b128 v[10:13], v0 offset:32
	ds_read_b128 v[112:115], v0
	s_waitcnt lgkmcnt(3)
	v_pk_mul_f32 v[76:77], v[76:77], v[2:3]
	s_waitcnt lgkmcnt(2)
	v_pk_mul_f32 v[72:73], v[72:73], v[6:7]
	s_waitcnt lgkmcnt(1)
	v_pk_mul_f32 v[68:69], v[68:69], v[10:11]
	v_pk_mul_f32 v[78:79], v[78:79], v[4:5]
	v_pk_mul_f32 v[74:75], v[74:75], v[8:9]
	v_pk_mul_f32 v[70:71], v[70:71], v[12:13]
	s_waitcnt lgkmcnt(0)
	v_pk_mul_f32 v[66:67], v[66:67], v[114:115]
	v_pk_mul_f32 v[64:65], v[64:65], v[112:113]
	v_pk_mul_f32 v[60:61], v[60:61], v[2:3]
	v_pk_mul_f32 v[56:57], v[56:57], v[6:7]
	v_pk_mul_f32 v[52:53], v[52:53], v[10:11]
	v_pk_mul_f32 v[62:63], v[62:63], v[4:5]
	v_pk_mul_f32 v[58:59], v[58:59], v[8:9]
	v_pk_mul_f32 v[54:55], v[54:55], v[12:13]
	v_pk_mul_f32 v[50:51], v[50:51], v[114:115]
	v_pk_mul_f32 v[48:49], v[48:49], v[112:113]
	v_pk_mul_f32 v[44:45], v[44:45], v[2:3]
	v_pk_mul_f32 v[40:41], v[40:41], v[6:7]
	v_pk_mul_f32 v[36:37], v[36:37], v[10:11]
	v_pk_mul_f32 v[46:47], v[46:47], v[4:5]
	v_pk_mul_f32 v[42:43], v[42:43], v[8:9]
	v_pk_mul_f32 v[38:39], v[38:39], v[12:13]
	v_pk_mul_f32 v[34:35], v[34:35], v[114:115]
	v_pk_mul_f32 v[32:33], v[32:33], v[112:113]
	v_pk_mul_f32 v[28:29], v[28:29], v[2:3]
	v_pk_mul_f32 v[24:25], v[24:25], v[6:7]
	v_pk_mul_f32 v[20:21], v[20:21], v[10:11]
	v_pk_mul_f32 v[30:31], v[30:31], v[4:5]
	v_pk_mul_f32 v[26:27], v[26:27], v[8:9]
	v_pk_mul_f32 v[22:23], v[22:23], v[12:13]
	v_pk_mul_f32 v[18:19], v[18:19], v[114:115]
	v_pk_mul_f32 v[16:17], v[16:17], v[112:113]

.LBB0_427:
	v_add_u32_e32 v14, s71, v234
	v_add_u32_e32 v0, s74, v233
	ds_read_b64_tr_b16 v[214:215], v14 offset:33280
	ds_read_b128 v[216:219], v0 offset:4096
	ds_read_b64_tr_b16 v[212:213], v14 offset:32768
	v_add_f32_e32 v2, v96, v97
	v_add_f32_e32 v2, v98, v2
	v_add_f32_e32 v2, v99, v2
	v_add_f32_e32 v2, v100, v2
	v_add_f32_e32 v2, v101, v2
	v_cvt_pk_bf16_f32 v188, v96, v97
	v_cvt_pk_bf16_f32 v189, v98, v99
	s_waitcnt lgkmcnt(3)
	v_mfma_f32_32x32x16_bf16 v[112:127], v[204:207], v[144:147], 0
	ds_read_b64_tr_b16 v[204:205], v14 offset:36864
	ds_read_b64_tr_b16 v[206:207], v14 offset:37376
	ds_read_b128 v[96:99], v0 offset:4608
	v_add_f32_e32 v2, v102, v2
	v_add_f32_e32 v2, v103, v2
	v_add_f32_e32 v2, v104, v2
	v_add_f32_e32 v6, v105, v2
	v_cvt_pk_bf16_f32 v190, v100, v101
	v_cvt_pk_bf16_f32 v191, v102, v103
	v_mfma_f32_32x32x16_bf16 v[128:143], v[196:199], v[144:147], 0
	ds_read_b64_tr_b16 v[4:5], v14 offset:34304
	ds_read_b128 v[100:103], v0 offset:6144
	ds_read_b64_tr_b16 v[2:3], v14 offset:33792
	v_add_f32_e32 v6, v106, v6
	v_add_f32_e32 v6, v107, v6
	v_add_f32_e32 v6, v108, v6
	v_add_f32_e32 v15, v109, v6
	v_cvt_pk_bf16_f32 v184, v104, v105
	v_cvt_pk_bf16_f32 v185, v106, v107
	s_waitcnt lgkmcnt(6)
	v_mfma_f32_32x32x16_bf16 v[112:127], v[200:203], v[148:151], v[112:127]
	ds_read_b64_tr_b16 v[6:7], v14 offset:37888
	ds_read_b64_tr_b16 v[8:9], v14 offset:38400
	ds_read_b128 v[104:107], v0 offset:6656
	v_add_f32_e32 v0, v110, v15
	v_add_f32_e32 v0, v111, v0
	v_add_f32_e32 v0, v80, v0
	v_add_f32_e32 v0, v81, v0
	v_cvt_pk_bf16_f32 v186, v108, v109
	v_cvt_pk_bf16_f32 v187, v110, v111
	v_mfma_f32_32x32x16_bf16 v[128:143], v[192:195], v[148:151], v[128:143]
	ds_read_b64_tr_b16 v[12:13], v14 offset:35328
	ds_read_b64_tr_b16 v[10:11], v14 offset:34816
	v_add_f32_e32 v0, v82, v0
	v_add_f32_e32 v0, v83, v0
	v_add_f32_e32 v0, v84, v0
	v_add_f32_e32 v0, v85, v0
	v_cvt_pk_bf16_f32 v180, v80, v81
	v_cvt_pk_bf16_f32 v181, v82, v83
	s_waitcnt lgkmcnt(5)
	v_mfma_f32_32x32x16_bf16 v[112:127], v[216:219], v[152:155], v[112:127]
	ds_read_b64_tr_b16 v[200:201], v14 offset:38912
	ds_read_b64_tr_b16 v[202:203], v14 offset:39424
	v_add_f32_e32 v0, v86, v0
	v_add_f32_e32 v0, v87, v0
	v_add_f32_e32 v0, v88, v0
	v_add_f32_e32 v0, v89, v0
	v_cvt_pk_bf16_f32 v182, v84, v85
	v_cvt_pk_bf16_f32 v183, v86, v87
	v_mfma_f32_32x32x16_bf16 v[128:143], v[96:99], v[152:155], v[128:143]
	ds_read_b64_tr_b16 v[196:197], v14 offset:35840
	ds_read_b64_tr_b16 v[198:199], v14 offset:36352
	v_add_f32_e32 v0, v90, v0
	v_add_f32_e32 v0, v91, v0
	v_add_f32_e32 v0, v92, v0
	v_add_f32_e32 v0, v93, v0
	v_cvt_pk_bf16_f32 v176, v88, v89
	v_cvt_pk_bf16_f32 v177, v90, v91
	s_waitcnt lgkmcnt(4)
	v_mfma_f32_32x32x16_bf16 v[112:127], v[100:103], v[156:159], v[112:127]
	ds_read_b64_tr_b16 v[192:193], v14 offset:39936
	ds_read_b64_tr_b16 v[194:195], v14 offset:40448
	v_add_f32_e32 v0, v94, v0
	v_add_f32_e32 v0, v95, v0
	v_add_f32_e32 v0, 0, v0
	v_cvt_pk_bf16_f32 v178, v92, v93
	v_cvt_pk_bf16_f32 v179, v94, v95
	v_mfma_f32_32x32x16_bf16 v[128:143], v[104:107], v[156:159], v[128:143]
	s_mov_b32 s0, 0
	s_nop 0
	v_add_f32_e32 v0, v241, v0
	v_mbcnt_lo_u32_b32 v15, -1, s0
	v_mbcnt_hi_u32_b32 v15, -1, v15
	v_and_or_b32 v95, v15, 31, s50
	v_ashrrev_i32_e32 v15, 5, v15
	s_nop 0
	v_lshlrev_b32_e32 v97, 2, v15
	v_add_u32_e32 v15, 0xe0, v97
	v_add_u32_e32 v81, 0xc0, v97
	v_cmp_le_i32_e32 vcc, v15, v95
	v_add_u32_e32 v82, 0xc2, v97
	v_add_u32_e32 v83, 0xc3, v97
	v_cndmask_b32_e32 v15, v250, v128, vcc
	v_cmp_lt_i32_e32 vcc, v81, v95
	v_add_u32_e32 v84, 0xc8, v97
	v_add_u32_e32 v85, 0xc9, v97
	v_cndmask_b32_e32 v80, v250, v113, vcc
	v_cmp_le_i32_e32 vcc, v81, v95
	v_add_u32_e32 v81, 0xe1, v97
	v_add_u32_e32 v86, 0xca, v97
	v_cndmask_b32_e32 v96, v250, v112, vcc
	v_cmp_le_i32_e32 vcc, v81, v95
	v_add_u32_e32 v87, 0xcb, v97
	v_add_u32_e32 v88, 0xd0, v97
	v_cndmask_b32_e32 v81, v250, v129, vcc
	v_cmp_le_i32_e32 vcc, v82, v95
	v_add_u32_e32 v82, 0xe2, v97
	v_add_u32_e32 v89, 0xd1, v97
	v_cndmask_b32_e32 v98, v250, v114, vcc
	v_cmp_le_i32_e32 vcc, v82, v95
	v_add_u32_e32 v90, 0xd2, v97
	v_add_u32_e32 v91, 0xd3, v97
	v_cndmask_b32_e32 v82, v250, v130, vcc
	v_cmp_le_i32_e32 vcc, v83, v95
	v_add_u32_e32 v83, 0xe3, v97
	v_add_u32_e32 v92, 0xd8, v97
	v_cndmask_b32_e32 v99, v250, v115, vcc
	v_cmp_le_i32_e32 vcc, v83, v95
	v_add_u32_e32 v93, 0xd9, v97
	v_add_u32_e32 v94, 0xda, v97
	v_cndmask_b32_e32 v83, v250, v131, vcc
	v_cmp_le_i32_e32 vcc, v84, v95
	v_add_u32_e32 v84, 0xe8, v97
	v_add_u32_e32 v111, 0xdb, v97
	v_cndmask_b32_e32 v100, v250, v116, vcc
	v_cmp_le_i32_e32 vcc, v84, v95
	v_max_f32_e32 v112, v96, v96
	s_nop 0
	v_cndmask_b32_e32 v84, v250, v132, vcc
	v_cmp_le_i32_e32 vcc, v85, v95
	v_add_u32_e32 v85, 0xe9, v97
	s_nop 0
	v_cndmask_b32_e32 v101, v250, v117, vcc
	v_cmp_le_i32_e32 vcc, v85, v95
	s_nop 1
	v_cndmask_b32_e32 v85, v250, v133, vcc
	v_cmp_le_i32_e32 vcc, v86, v95
	v_add_u32_e32 v86, 0xea, v97
	s_nop 0
	v_cndmask_b32_e32 v102, v250, v118, vcc
	v_cmp_le_i32_e32 vcc, v86, v95
	s_nop 1
	v_cndmask_b32_e32 v86, v250, v134, vcc
	v_cmp_le_i32_e32 vcc, v87, v95
	v_add_u32_e32 v87, 0xeb, v97
	s_nop 0
	v_cndmask_b32_e32 v103, v250, v119, vcc
	v_cmp_le_i32_e32 vcc, v87, v95
	s_nop 1
	v_cndmask_b32_e32 v87, v250, v135, vcc
	v_cmp_le_i32_e32 vcc, v88, v95
	v_add_u32_e32 v88, 0xf0, v97
	s_nop 0
	v_cndmask_b32_e32 v104, v250, v120, vcc
	v_cmp_le_i32_e32 vcc, v88, v95
	s_nop 1
	v_cndmask_b32_e32 v88, v250, v136, vcc
	v_cmp_le_i32_e32 vcc, v89, v95
	v_add_u32_e32 v89, 0xf1, v97
	s_nop 0
	v_cndmask_b32_e32 v105, v250, v121, vcc
	v_cmp_le_i32_e32 vcc, v89, v95
	s_nop 1
	v_cndmask_b32_e32 v89, v250, v137, vcc
	v_cmp_le_i32_e32 vcc, v90, v95
	v_add_u32_e32 v90, 0xf2, v97
	s_nop 0
	v_cndmask_b32_e32 v106, v250, v122, vcc
	v_cmp_le_i32_e32 vcc, v90, v95
	s_nop 1
	v_cndmask_b32_e32 v90, v250, v138, vcc
	v_cmp_le_i32_e32 vcc, v91, v95
	v_add_u32_e32 v91, 0xf3, v97
	s_nop 0
	v_cndmask_b32_e32 v107, v250, v123, vcc
	v_cmp_le_i32_e32 vcc, v91, v95
	s_nop 1
	v_cndmask_b32_e32 v91, v250, v139, vcc
	v_cmp_le_i32_e32 vcc, v92, v95
	v_add_u32_e32 v92, 0xf8, v97
	s_nop 0
	v_cndmask_b32_e32 v108, v250, v124, vcc
	v_cmp_le_i32_e32 vcc, v92, v95
	s_nop 1
	v_cndmask_b32_e32 v92, v250, v140, vcc
	v_cmp_le_i32_e32 vcc, v93, v95
	v_add_u32_e32 v93, 0xf9, v97
	s_nop 0
	v_cndmask_b32_e32 v109, v250, v125, vcc
	v_cmp_le_i32_e32 vcc, v93, v95
	s_nop 1
	v_cndmask_b32_e32 v93, v250, v141, vcc
	v_cmp_le_i32_e32 vcc, v94, v95
	v_add_u32_e32 v94, 0xfa, v97
	v_add_u32_e32 v97, 0xfb, v97
	v_cndmask_b32_e32 v110, v250, v126, vcc
	v_cmp_le_i32_e32 vcc, v94, v95
	s_nop 1
	v_cndmask_b32_e32 v94, v250, v142, vcc
	v_cmp_le_i32_e32 vcc, v111, v95
	s_nop 1
	v_cndmask_b32_e32 v111, v250, v127, vcc
	v_cmp_le_i32_e32 vcc, v97, v95
	v_max_f32_e32 v97, v80, v80
	v_max_f32_e32 v97, v112, v97
	v_max3_f32 v112, v98, v99, v81
	v_max3_f32 v97, v97, v15, v82
	v_max3_f32 v97, v97, v83, v100
	v_max3_f32 v112, v112, v102, v103
	v_max3_f32 v97, v97, v101, v84
	v_max3_f32 v112, v112, v86, v87
	v_max3_f32 v97, v97, v85, v104
	v_max3_f32 v112, v112, v106, v107
	v_max3_f32 v97, v97, v105, v88
	v_max3_f32 v112, v112, v90, v91
	v_cndmask_b32_e32 v95, v250, v143, vcc
	v_max3_f32 v97, v97, v89, v108
	v_max3_f32 v112, v112, v110, v111
	v_max3_f32 v97, v97, v109, v92
	v_max3_f32 v112, v112, v94, v95
	v_max3_f32 v97, v97, v93, v112
	v_mov_b32_e32 v112, v97
	s_nop 1
	v_permlane32_swap_b32_e32 v97, v112
	v_max_f32_e32 v112, v112, v112
	v_max_f32_e32 v97, v97, v97
	v_max_f32_e32 v97, v97, v112
	v_sub_f32_e32 v97, v97, v239
	v_cmp_lt_f32_e32 vcc, s87, v97
	s_cmp_lg_u64 vcc, 0
	s_cselect_b64 s[0:1], -1, 0
	s_cbranch_vccnz .LBB0_490

.LBB0_440:
	s_waitcnt lgkmcnt(0)
	s_add_i32 s72, s5, -3
	s_add_i32 s0, s72, 1
	s_cmp_ge_u32 s0, s48
	s_cbranch_scc1 .LBB0_426

.LBB0_442:
	v_add_u32_e32 v14, s4, v234
	v_add_u32_e32 v0, s74, v233
	ds_read_b64_tr_b16 v[214:215], v14 offset:33280
	ds_read_b128 v[216:219], v0 offset:4096
	ds_read_b64_tr_b16 v[212:213], v14 offset:32768
	s_waitcnt lgkmcnt(3)
	v_mfma_f32_32x32x16_bf16 v[128:143], v[204:207], v[144:147], 0
	v_add_f32_e32 v2, v96, v97
	v_add_f32_e32 v2, v98, v2
	v_add_f32_e32 v2, v99, v2
	v_add_f32_e32 v2, v100, v2
	v_add_f32_e32 v2, v101, v2
	v_cvt_pk_bf16_f32 v188, v96, v97
	v_cvt_pk_bf16_f32 v189, v98, v99
	ds_read_b64_tr_b16 v[204:205], v14 offset:36864
	ds_read_b64_tr_b16 v[206:207], v14 offset:37376
	ds_read_b128 v[226:229], v0 offset:4608
	v_mfma_f32_32x32x16_bf16 v[112:127], v[196:199], v[144:147], 0
	v_add_f32_e32 v2, v102, v2
	v_add_f32_e32 v2, v103, v2
	v_add_f32_e32 v2, v104, v2
	v_add_f32_e32 v6, v105, v2
	v_cvt_pk_bf16_f32 v190, v100, v101
	v_cvt_pk_bf16_f32 v191, v102, v103
	ds_read_b64_tr_b16 v[4:5], v14 offset:34304
	ds_read_b128 v[100:103], v0 offset:6144
	ds_read_b64_tr_b16 v[2:3], v14 offset:33792
	s_waitcnt lgkmcnt(6)
	v_mfma_f32_32x32x16_bf16 v[128:143], v[200:203], v[148:151], v[128:143]
	v_add_f32_e32 v6, v106, v6
	v_add_f32_e32 v6, v107, v6
	v_add_f32_e32 v6, v108, v6
	v_add_f32_e32 v15, v109, v6
	v_cvt_pk_bf16_f32 v184, v104, v105
	v_cvt_pk_bf16_f32 v185, v106, v107
	ds_read_b64_tr_b16 v[6:7], v14 offset:37888
	ds_read_b64_tr_b16 v[8:9], v14 offset:38400
	ds_read_b128 v[104:107], v0 offset:6656
	v_mfma_f32_32x32x16_bf16 v[112:127], v[192:195], v[148:151], v[112:127]
	v_add_f32_e32 v0, v110, v15
	v_add_f32_e32 v0, v111, v0
	v_add_f32_e32 v0, v80, v0
	v_add_f32_e32 v0, v81, v0
	v_cvt_pk_bf16_f32 v186, v108, v109
	v_cvt_pk_bf16_f32 v187, v110, v111
	ds_read_b64_tr_b16 v[12:13], v14 offset:35328
	ds_read_b64_tr_b16 v[10:11], v14 offset:34816
	s_waitcnt lgkmcnt(5)
	v_mfma_f32_32x32x16_bf16 v[128:143], v[216:219], v[152:155], v[128:143]
	v_add_f32_e32 v0, v82, v0
	v_add_f32_e32 v0, v83, v0
	v_add_f32_e32 v0, v84, v0
	v_add_f32_e32 v0, v85, v0
	v_cvt_pk_bf16_f32 v180, v80, v81
	v_cvt_pk_bf16_f32 v181, v82, v83
	ds_read_b64_tr_b16 v[96:97], v14 offset:38912
	ds_read_b64_tr_b16 v[98:99], v14 offset:39424
	v_mfma_f32_32x32x16_bf16 v[112:127], v[226:229], v[152:155], v[112:127]
	v_add_f32_e32 v0, v86, v0
	v_add_f32_e32 v0, v87, v0
	v_add_f32_e32 v0, v88, v0
	v_add_f32_e32 v0, v89, v0
	v_cvt_pk_bf16_f32 v182, v84, v85
	v_cvt_pk_bf16_f32 v183, v86, v87
	ds_read_b64_tr_b16 v[84:85], v14 offset:35840
	ds_read_b64_tr_b16 v[86:87], v14 offset:36352
	s_waitcnt lgkmcnt(4)
	v_mfma_f32_32x32x16_bf16 v[128:143], v[100:103], v[156:159], v[128:143]
	v_add_f32_e32 v0, v90, v0
	v_add_f32_e32 v0, v91, v0
	v_add_f32_e32 v0, v92, v0
	v_add_f32_e32 v0, v93, v0
	v_cvt_pk_bf16_f32 v176, v88, v89
	v_cvt_pk_bf16_f32 v177, v90, v91
	ds_read_b64_tr_b16 v[80:81], v14 offset:39936
	ds_read_b64_tr_b16 v[82:83], v14 offset:40448
	v_mfma_f32_32x32x16_bf16 v[112:127], v[104:107], v[156:159], v[112:127]
	v_add_f32_e32 v0, v94, v0
	v_add_f32_e32 v0, v95, v0
	v_add_f32_e32 v0, 0, v0
	v_cvt_pk_bf16_f32 v178, v92, v93
	v_cvt_pk_bf16_f32 v179, v94, v95
	s_add_i32 s0, s72, 3
	s_cmp_ge_u32 s0, s48
	s_cselect_b64 s[0:1], -1, 0
	s_and_b64 vcc, exec, s[0:1]
	s_cbranch_vccnz .LBB0_444
	s_add_u32 s2, s24, 0x10000
	s_addc_u32 s3, s25, 0
	s_add_i32 s4, s74, 0xffffe000
	s_cmp_lg_u32 s74, 0
	s_cselect_b32 s4, s4, 0x6000
	s_add_i32 s4, s4, s46
	s_mov_b32 s5, m0
	s_mov_b32 m0, s4
	s_nop 3
	global_load_lds_dwordx4 v236, s[24:25]
	s_mov_b32 m0, s5
	s_mov_b64 s[24:25], s[2:3]

.LBB0_447:
	v_mfma_f32_32x32x16_bf16 v[64:79], v[188:191], v[212:215], v[64:79]
	v_sub_f32_e32 v15, v128, v239
	v_exp_f32_e32 v128, v15
	v_sub_f32_e32 v15, v129, v239
	v_exp_f32_e32 v129, v15
	ds_read_b64_tr_b16 v[88:89], v14 offset:40960
	ds_read_b64_tr_b16 v[90:91], v14 offset:41472
	v_mfma_f32_32x32x16_bf16 v[48:63], v[188:191], v[204:207], v[48:63]
	v_sub_f32_e32 v15, v130, v239
	v_exp_f32_e32 v130, v15
	v_sub_f32_e32 v15, v131, v239
	v_exp_f32_e32 v131, v15
	ds_read_b64_tr_b16 v[92:93], v14 offset:45056
	ds_read_b64_tr_b16 v[94:95], v14 offset:45568
	v_mfma_f32_32x32x16_bf16 v[64:79], v[184:187], v[2:5], v[64:79]
	v_sub_f32_e32 v2, v132, v239
	v_exp_f32_e32 v132, v2
	v_sub_f32_e32 v2, v133, v239
	v_exp_f32_e32 v133, v2
	ds_read_b64_tr_b16 v[2:3], v14 offset:41984
	ds_read_b64_tr_b16 v[4:5], v14 offset:42496
	v_mfma_f32_32x32x16_bf16 v[48:63], v[184:187], v[6:9], v[48:63]
	v_sub_f32_e32 v6, v134, v239
	v_exp_f32_e32 v134, v6
	v_sub_f32_e32 v6, v135, v239
	v_exp_f32_e32 v135, v6
	ds_read_b64_tr_b16 v[6:7], v14 offset:46080
	ds_read_b64_tr_b16 v[8:9], v14 offset:46592
	v_mfma_f32_32x32x16_bf16 v[64:79], v[180:183], v[10:13], v[64:79]
	v_sub_f32_e32 v10, v136, v239
	v_exp_f32_e32 v136, v10
	v_sub_f32_e32 v10, v137, v239
	v_exp_f32_e32 v137, v10
	ds_read_b64_tr_b16 v[10:11], v14 offset:43008
	ds_read_b64_tr_b16 v[12:13], v14 offset:43520
	s_waitcnt lgkmcnt(14)
	v_mfma_f32_32x32x16_bf16 v[48:63], v[180:183], v[96:99], v[48:63]
	v_sub_f32_e32 v15, v138, v239
	v_exp_f32_e32 v138, v15
	v_sub_f32_e32 v15, v139, v239
	v_exp_f32_e32 v139, v15
	ds_read_b64_tr_b16 v[96:97], v14 offset:47104
	ds_read_b64_tr_b16 v[98:99], v14 offset:47616
	s_waitcnt lgkmcnt(14)
	v_mfma_f32_32x32x16_bf16 v[64:79], v[176:179], v[84:87], v[64:79]
	v_sub_f32_e32 v15, v140, v239
	v_exp_f32_e32 v140, v15
	v_sub_f32_e32 v15, v141, v239
	v_exp_f32_e32 v141, v15
	ds_read_b64_tr_b16 v[84:85], v14 offset:44032
	ds_read_b64_tr_b16 v[86:87], v14 offset:44544
	s_waitcnt lgkmcnt(14)
	v_mfma_f32_32x32x16_bf16 v[48:63], v[176:179], v[80:83], v[48:63]
	v_sub_f32_e32 v15, v142, v239
	v_exp_f32_e32 v142, v15
	v_sub_f32_e32 v15, v143, v239
	v_exp_f32_e32 v143, v15
	ds_read_b64_tr_b16 v[80:81], v14 offset:48128
	ds_read_b64_tr_b16 v[82:83], v14 offset:48640
	s_waitcnt lgkmcnt(14)
	v_mfma_f32_32x32x16_bf16 v[32:47], v[188:191], v[88:91], v[32:47]
	v_sub_f32_e32 v14, v112, v239
	v_exp_f32_e32 v112, v14
	v_sub_f32_e32 v14, v113, v239
	v_exp_f32_e32 v113, v14
	s_waitcnt lgkmcnt(12)
	v_mfma_f32_32x32x16_bf16 v[16:31], v[188:191], v[92:95], v[16:31]
	v_sub_f32_e32 v14, v114, v239
	v_exp_f32_e32 v114, v14
	v_sub_f32_e32 v14, v115, v239
	v_exp_f32_e32 v115, v14
	s_waitcnt lgkmcnt(10)
	v_mfma_f32_32x32x16_bf16 v[32:47], v[184:187], v[2:5], v[32:47]
	v_sub_f32_e32 v2, v116, v239
	v_exp_f32_e32 v116, v2
	v_sub_f32_e32 v2, v117, v239
	v_exp_f32_e32 v117, v2
	s_waitcnt lgkmcnt(8)
	v_mfma_f32_32x32x16_bf16 v[16:31], v[184:187], v[6:9], v[16:31]
	v_sub_f32_e32 v2, v118, v239
	v_exp_f32_e32 v118, v2
	v_sub_f32_e32 v2, v119, v239
	v_exp_f32_e32 v119, v2
	v_add_u32_e32 v6, s70, v233
	ds_read_b128 v[204:207], v6
	s_waitcnt lgkmcnt(7)
	v_mfma_f32_32x32x16_bf16 v[32:47], v[180:183], v[10:13], v[32:47]
	v_sub_f32_e32 v2, v120, v239
	v_exp_f32_e32 v120, v2
	v_sub_f32_e32 v2, v121, v239
	v_exp_f32_e32 v121, v2
	ds_read_b128 v[196:199], v6 offset:512
	s_waitcnt lgkmcnt(6)
	v_mfma_f32_32x32x16_bf16 v[16:31], v[180:183], v[96:99], v[16:31]
	v_sub_f32_e32 v2, v122, v239
	v_exp_f32_e32 v122, v2
	v_sub_f32_e32 v2, v123, v239
	v_exp_f32_e32 v123, v2
	ds_read_b128 v[200:203], v6 offset:2048
	s_waitcnt lgkmcnt(5)
	v_mfma_f32_32x32x16_bf16 v[32:47], v[176:179], v[84:87], v[32:47]
	v_sub_f32_e32 v2, v124, v239
	v_exp_f32_e32 v124, v2
	v_sub_f32_e32 v2, v125, v239
	v_exp_f32_e32 v125, v2
	ds_read_b128 v[192:195], v6 offset:2560
	s_waitcnt lgkmcnt(4)
	v_mfma_f32_32x32x16_bf16 v[16:31], v[176:179], v[80:83], v[16:31]
	v_sub_f32_e32 v7, v126, v239
	v_exp_f32_e32 v126, v7
	v_sub_f32_e32 v7, v127, v239
	v_exp_f32_e32 v127, v7
	s_mov_b64 s[4:5], -1
	s_and_b64 vcc, exec, s[0:1]
	s_cbranch_vccnz .LBB0_455
	s_andn2_b64 vcc, exec, s[4:5]
	s_cbranch_vccz .LBB0_460

.LBB0_451:
	v_add_u32_e32 v14, s69, v234
	ds_read_b64_tr_b16 v[216:217], v14 offset:32768
	ds_read_b64_tr_b16 v[218:219], v14 offset:33280
	ds_read_b128 v[10:13], v6 offset:4096
	s_waitcnt lgkmcnt(3)
	v_mfma_f32_32x32x16_bf16 v[96:111], v[204:207], v[144:147], 0
	v_add_f32_e32 v7, v128, v129
	v_add_f32_e32 v7, v130, v7
	v_add_f32_e32 v7, v131, v7
	v_add_f32_e32 v7, v132, v7
	v_add_f32_e32 v7, v133, v7
	v_cvt_pk_bf16_f32 v188, v128, v129
	v_cvt_pk_bf16_f32 v189, v130, v131
	ds_read_b64_tr_b16 v[214:215], v14 offset:37376
	ds_read_b64_tr_b16 v[212:213], v14 offset:36864
	ds_read_b128 v[246:249], v6 offset:4608
	v_mfma_f32_32x32x16_bf16 v[80:95], v[196:199], v[144:147], 0
	v_add_f32_e32 v7, v134, v7
	v_add_f32_e32 v7, v135, v7
	v_add_f32_e32 v7, v136, v7
	v_add_f32_e32 v7, v137, v7
	v_cvt_pk_bf16_f32 v190, v132, v133
	v_cvt_pk_bf16_f32 v191, v134, v135
	ds_read_b64_tr_b16 v[132:133], v14 offset:33792
	ds_read_b64_tr_b16 v[134:135], v14 offset:34304
	ds_read_b128 v[242:245], v6 offset:6144
	s_waitcnt lgkmcnt(6)
	v_mfma_f32_32x32x16_bf16 v[96:111], v[200:203], v[148:151], v[96:111]
	v_add_f32_e32 v2, v138, v7
	v_add_f32_e32 v2, v139, v2
	v_add_f32_e32 v2, v140, v2
	v_add_f32_e32 v7, v141, v2
	v_cvt_pk_bf16_f32 v184, v136, v137
	v_cvt_pk_bf16_f32 v185, v138, v139
	ds_read_b64_tr_b16 v[4:5], v14 offset:38400
	ds_read_b64_tr_b16 v[2:3], v14 offset:37888
	ds_read_b128 v[136:139], v6 offset:6656
	v_mfma_f32_32x32x16_bf16 v[80:95], v[192:195], v[148:151], v[80:95]
	v_add_f32_e32 v6, v142, v7
	v_add_f32_e32 v6, v143, v6
	v_add_f32_e32 v6, v112, v6
	v_add_f32_e32 v15, v113, v6
	v_cvt_pk_bf16_f32 v186, v140, v141
	v_cvt_pk_bf16_f32 v187, v142, v143
	ds_read_b64_tr_b16 v[8:9], v14 offset:35328
	ds_read_b64_tr_b16 v[6:7], v14 offset:34816
	s_waitcnt lgkmcnt(5)
	v_mfma_f32_32x32x16_bf16 v[96:111], v[10:13], v[152:155], v[96:111]
	v_add_f32_e32 v10, v114, v15
	v_add_f32_e32 v10, v115, v10
	v_add_f32_e32 v10, v116, v10
	v_add_f32_e32 v10, v117, v10
	v_cvt_pk_bf16_f32 v180, v112, v113
	v_cvt_pk_bf16_f32 v181, v114, v115
	ds_read_b64_tr_b16 v[128:129], v14 offset:38912
	ds_read_b64_tr_b16 v[130:131], v14 offset:39424
	v_mfma_f32_32x32x16_bf16 v[80:95], v[246:249], v[152:155], v[80:95]
	v_add_f32_e32 v10, v118, v10
	v_add_f32_e32 v10, v119, v10
	v_add_f32_e32 v10, v120, v10
	v_add_f32_e32 v10, v121, v10
	v_cvt_pk_bf16_f32 v182, v116, v117
	v_cvt_pk_bf16_f32 v183, v118, v119
	ds_read_b64_tr_b16 v[112:113], v14 offset:35840
	ds_read_b64_tr_b16 v[114:115], v14 offset:36352
	s_waitcnt lgkmcnt(4)
	v_mfma_f32_32x32x16_bf16 v[96:111], v[242:245], v[156:159], v[96:111]
	v_add_f32_e32 v10, v122, v10
	v_add_f32_e32 v10, v123, v10
	v_add_f32_e32 v10, v124, v10
	v_add_f32_e32 v15, v125, v10
	v_cvt_pk_bf16_f32 v176, v120, v121
	v_cvt_pk_bf16_f32 v177, v122, v123
	ds_read_b64_tr_b16 v[10:11], v14 offset:39936
	ds_read_b64_tr_b16 v[12:13], v14 offset:40448
	v_mfma_f32_32x32x16_bf16 v[80:95], v[136:139], v[156:159], v[80:95]
	v_add_f32_e32 v15, v126, v15
	v_add_f32_e32 v15, v127, v15
	v_add_f32_e32 v15, 0, v15
	v_cvt_pk_bf16_f32 v178, v124, v125
	v_cvt_pk_bf16_f32 v179, v126, v127
	s_add_i32 s2, s72, 4
	s_cmp_ge_u32 s2, s48
	s_cselect_b64 s[2:3], -1, 0
	s_and_b64 vcc, exec, s[2:3]
	s_cbranch_vccnz .LBB0_453
	s_add_u32 s4, s24, 0x10000
	s_addc_u32 s5, s25, 0
	s_add_i32 s40, s70, 0xffffe000
	s_cmp_lg_u32 s70, 0
	s_cselect_b32 s40, s40, 0x6000
	s_add_i32 s40, s40, s46
	s_mov_b32 s41, m0
	s_mov_b32 m0, s40
	s_nop 3
	global_load_lds_dwordx4 v236, s[24:25]
	s_mov_b32 m0, s41
	s_mov_b64 s[24:25], s[4:5]

.LBB0_470:
	s_waitcnt lgkmcnt(2)
	v_mfma_f32_32x32x16_bf16 v[32:47], v[176:179], v[6:9], v[32:47]
	v_sub_f32_e32 v6, v92, v239
	v_exp_f32_e32 v92, v6
	v_sub_f32_e32 v6, v93, v239
	v_exp_f32_e32 v93, v6
	s_and_b64 vcc, exec, s[4:5]
	s_cbranch_vccnz .LBB0_472
	ds_read_b128 v[192:195], v0 offset:2560
.LBB0_472:
	s_waitcnt lgkmcnt(0)
	v_mfma_f32_32x32x16_bf16 v[16:31], v[176:179], v[2:5], v[16:31]
	v_sub_f32_e32 v0, v94, v239
	v_exp_f32_e32 v94, v0
	v_sub_f32_e32 v0, v95, v239
	v_exp_f32_e32 v95, v0
	s_mov_b64 s[4:5], -1
	s_and_b64 vcc, exec, s[2:3]
	s_cbranch_vccnz .LBB0_478
	s_andn2_b64 vcc, exec, s[4:5]
	s_cbranch_vccz .LBB0_483
